# A15: A13 + scan y reduced once per 4 tokens, deferred into the next group (2 LDS writes per 4 tokens)
# baseline (speedup 1.0000x reference)
.Lrw_scan_loop:
	s_and_b32 s2, s8, 1
	s_mul_i32 s3, s2, 0xe000
	s_lshl_b32 s2, s2, 12
	v_add_u32_e32 v195, s3, v103
	v_add_u32_e32 v33, s3, v38
	v_add_u32_e32 v196, s3, v75
	v_add_u32_e32 v36, s3, v37
	v_add_u32_e32 v102, s2, v76
	ds_read_b128 v[140:143], v195 offset:0
	ds_read_b128 v[152:155], v195 offset:8192
	ds_read_b128 v[176:179], v195 offset:16384
	ds_read_b128 v[84:87], v195 offset:32768
	ds_read_b64 v[4:5], v196 offset:0
	ds_read_b32 v6, v36 offset:0
	ds_read_b128 v[144:147], v195 offset:256
	ds_read_b128 v[156:159], v195 offset:8448
	ds_read_b128 v[180:183], v195 offset:16640
	ds_read_b128 v[88:91], v195 offset:33024
	ds_read_b64 v[8:9], v196 offset:512
	ds_read_b32 v10, v36 offset:512
	s_waitcnt lgkmcnt(6)
	v_pk_mul_f32 v[46:47], v[24:25], v[140:141] op_sel_hi:[0,1]
	v_pk_mul_f32 v[34:35], v[20:21], v[140:141] op_sel_hi:[0,1]
	v_pk_fma_f32 v[46:47], v[24:25], v[142:143], v[46:47] op_sel:[1,0,0] op_sel_hi:[1,1,1]
	v_pk_fma_f32 v[34:35], v[20:21], v[142:143], v[34:35] op_sel:[1,0,0] op_sel_hi:[1,1,1]
	v_pk_fma_f32 v[46:47], v[26:27], v[152:153], v[46:47] op_sel_hi:[0,1,1]
	v_pk_fma_f32 v[34:35], v[22:23], v[152:153], v[34:35] op_sel_hi:[0,1,1]
	v_pk_fma_f32 v[46:47], v[26:27], v[154:155], v[46:47] op_sel:[1,0,0] op_sel_hi:[1,1,1]
	v_pk_fma_f32 v[34:35], v[22:23], v[154:155], v[34:35] op_sel:[1,0,0] op_sel_hi:[1,1,1]
	v_pk_fma_f32 v[20:21], v[176:177], v[4:5], v[20:21] op_sel_hi:[1,0,1]
	v_add_f32_dpp v28, v46, v34 row_half_mirror row_mask:0xf bank_mask:0xf
	v_add_f32_dpp v148, v47, v35 row_half_mirror row_mask:0xf bank_mask:0xf
	v_pk_fma_f32 v[22:23], v[178:179], v[4:5], v[22:23] op_sel_hi:[1,0,1]
	v_add_f32_dpp v28, v28, v28 row_ror:8 row_mask:0xf bank_mask:0xf
	v_pk_fma_f32 v[24:25], v[176:177], v[6:7], v[24:25] op_sel_hi:[1,0,1]
	v_pk_fma_f32 v[26:27], v[178:179], v[6:7], v[26:27] op_sel_hi:[1,0,1]
	v_add_f32_dpp v28, v28, v28 quad_perm:[1,0,3,2] row_mask:0xf bank_mask:0xf
	v_fmac_f32_e32 v148, 0x3e000000, v5
	s_nop 0
	v_add_f32_dpp v28, v28, v28 quad_perm:[2,3,0,1] row_mask:0xf bank_mask:0xf
	v_pk_fma_f32 v[20:21], v[84:85], v[28:29], v[20:21] op_sel_hi:[1,0,1] neg_lo:[0,1,0] neg_hi:[0,1,0]
	v_pk_fma_f32 v[22:23], v[86:87], v[28:29], v[22:23] op_sel_hi:[1,0,1] neg_lo:[0,1,0] neg_hi:[0,1,0]
	v_mov_b32_dpp v30, v28 row_half_mirror row_mask:0xf bank_mask:0xf
	v_pk_fma_f32 v[24:25], v[84:85], v[30:31], v[24:25] op_sel_hi:[1,0,1] neg_lo:[0,1,0] neg_hi:[0,1,0]
	v_pk_fma_f32 v[26:27], v[86:87], v[30:31], v[26:27] op_sel_hi:[1,0,1] neg_lo:[0,1,0] neg_hi:[0,1,0]
	ds_read_b128 v[140:143], v195 offset:512
	ds_read_b128 v[152:155], v195 offset:8704
	ds_read_b128 v[176:179], v195 offset:16896
	ds_read_b128 v[84:87], v195 offset:33280
	ds_read_b64 v[4:5], v196 offset:1024
	ds_read_b32 v6, v36 offset:1024
	s_waitcnt lgkmcnt(6)
	v_pk_mul_f32 v[46:47], v[24:25], v[144:145] op_sel_hi:[0,1]
	v_pk_mul_f32 v[34:35], v[20:21], v[144:145] op_sel_hi:[0,1]
	v_pk_fma_f32 v[46:47], v[24:25], v[146:147], v[46:47] op_sel:[1,0,0] op_sel_hi:[1,1,1]
	v_pk_fma_f32 v[34:35], v[20:21], v[146:147], v[34:35] op_sel:[1,0,0] op_sel_hi:[1,1,1]
	v_pk_fma_f32 v[46:47], v[26:27], v[156:157], v[46:47] op_sel_hi:[0,1,1]
	v_pk_fma_f32 v[34:35], v[22:23], v[156:157], v[34:35] op_sel_hi:[0,1,1]
	v_pk_fma_f32 v[46:47], v[26:27], v[158:159], v[46:47] op_sel:[1,0,0] op_sel_hi:[1,1,1]
	v_pk_fma_f32 v[34:35], v[22:23], v[158:159], v[34:35] op_sel:[1,0,0] op_sel_hi:[1,1,1]
	v_pk_fma_f32 v[20:21], v[180:181], v[8:9], v[20:21] op_sel_hi:[1,0,1]
	v_add_f32_dpp v28, v46, v34 row_half_mirror row_mask:0xf bank_mask:0xf
	v_add_f32_dpp v149, v47, v35 row_half_mirror row_mask:0xf bank_mask:0xf
	v_pk_fma_f32 v[22:23], v[182:183], v[8:9], v[22:23] op_sel_hi:[1,0,1]
	v_add_f32_dpp v28, v28, v28 row_ror:8 row_mask:0xf bank_mask:0xf
	v_pk_fma_f32 v[24:25], v[180:181], v[10:11], v[24:25] op_sel_hi:[1,0,1]
	v_pk_fma_f32 v[26:27], v[182:183], v[10:11], v[26:27] op_sel_hi:[1,0,1]
	v_add_f32_dpp v28, v28, v28 quad_perm:[1,0,3,2] row_mask:0xf bank_mask:0xf
	v_fmac_f32_e32 v149, 0x3e000000, v9
	s_nop 0
	v_add_f32_dpp v28, v28, v28 quad_perm:[2,3,0,1] row_mask:0xf bank_mask:0xf
	v_pk_fma_f32 v[20:21], v[88:89], v[28:29], v[20:21] op_sel_hi:[1,0,1] neg_lo:[0,1,0] neg_hi:[0,1,0]
	v_pk_fma_f32 v[22:23], v[90:91], v[28:29], v[22:23] op_sel_hi:[1,0,1] neg_lo:[0,1,0] neg_hi:[0,1,0]
	v_mov_b32_dpp v30, v28 row_half_mirror row_mask:0xf bank_mask:0xf
	v_pk_fma_f32 v[24:25], v[88:89], v[30:31], v[24:25] op_sel_hi:[1,0,1] neg_lo:[0,1,0] neg_hi:[0,1,0]
	v_pk_fma_f32 v[26:27], v[90:91], v[30:31], v[26:27] op_sel_hi:[1,0,1] neg_lo:[0,1,0] neg_hi:[0,1,0]
	ds_read_b128 v[144:147], v195 offset:768
	ds_read_b128 v[156:159], v195 offset:8960
	ds_read_b128 v[168:171], v195 offset:25344
	ds_read_b128 v[180:183], v195 offset:17152
	ds_read_b128 v[88:91], v195 offset:33536
	ds_read_b64 v[8:9], v196 offset:1536
	ds_read_b32 v10, v36 offset:1536
	s_waitcnt lgkmcnt(7)
	v_pk_mul_f32 v[46:47], v[24:25], v[140:141] op_sel_hi:[0,1]
	v_pk_mul_f32 v[34:35], v[20:21], v[140:141] op_sel_hi:[0,1]
	v_pk_fma_f32 v[46:47], v[24:25], v[142:143], v[46:47] op_sel:[1,0,0] op_sel_hi:[1,1,1]
	v_pk_fma_f32 v[34:35], v[20:21], v[142:143], v[34:35] op_sel:[1,0,0] op_sel_hi:[1,1,1]
	v_pk_fma_f32 v[46:47], v[26:27], v[152:153], v[46:47] op_sel_hi:[0,1,1]
	v_pk_fma_f32 v[34:35], v[22:23], v[152:153], v[34:35] op_sel_hi:[0,1,1]
	v_pk_fma_f32 v[46:47], v[26:27], v[154:155], v[46:47] op_sel:[1,0,0] op_sel_hi:[1,1,1]
	v_pk_fma_f32 v[34:35], v[22:23], v[154:155], v[34:35] op_sel:[1,0,0] op_sel_hi:[1,1,1]
	v_pk_fma_f32 v[20:21], v[176:177], v[4:5], v[20:21] op_sel_hi:[1,0,1]
	v_add_f32_dpp v28, v46, v34 row_half_mirror row_mask:0xf bank_mask:0xf
	v_add_f32_dpp v150, v47, v35 row_half_mirror row_mask:0xf bank_mask:0xf
	v_pk_fma_f32 v[22:23], v[178:179], v[4:5], v[22:23] op_sel_hi:[1,0,1]
	v_add_f32_dpp v28, v28, v28 row_ror:8 row_mask:0xf bank_mask:0xf
	v_pk_fma_f32 v[24:25], v[176:177], v[6:7], v[24:25] op_sel_hi:[1,0,1]
	v_pk_fma_f32 v[26:27], v[178:179], v[6:7], v[26:27] op_sel_hi:[1,0,1]
	v_add_f32_dpp v28, v28, v28 quad_perm:[1,0,3,2] row_mask:0xf bank_mask:0xf
	v_fmac_f32_e32 v150, 0x3e000000, v5
	s_nop 0
	v_add_f32_dpp v28, v28, v28 quad_perm:[2,3,0,1] row_mask:0xf bank_mask:0xf
	v_pk_fma_f32 v[20:21], v[84:85], v[28:29], v[20:21] op_sel_hi:[1,0,1] neg_lo:[0,1,0] neg_hi:[0,1,0]
	v_pk_fma_f32 v[22:23], v[86:87], v[28:29], v[22:23] op_sel_hi:[1,0,1] neg_lo:[0,1,0] neg_hi:[0,1,0]
	v_mov_b32_dpp v30, v28 row_half_mirror row_mask:0xf bank_mask:0xf
	v_pk_fma_f32 v[24:25], v[84:85], v[30:31], v[24:25] op_sel_hi:[1,0,1] neg_lo:[0,1,0] neg_hi:[0,1,0]
	v_pk_fma_f32 v[26:27], v[86:87], v[30:31], v[26:27] op_sel_hi:[1,0,1] neg_lo:[0,1,0] neg_hi:[0,1,0]
	ds_read_b128 v[140:143], v195 offset:1024
	ds_read_b128 v[152:155], v195 offset:9216
	ds_read_b128 v[176:179], v195 offset:17408
	ds_read_b128 v[84:87], v195 offset:33792
	ds_read_b64 v[4:5], v196 offset:2048
	ds_read_b32 v6, v36 offset:2048
	s_waitcnt lgkmcnt(6)
	v_pk_mul_f32 v[46:47], v[24:25], v[144:145] op_sel_hi:[0,1]
	v_pk_mul_f32 v[34:35], v[20:21], v[144:145] op_sel_hi:[0,1]
	v_pk_fma_f32 v[46:47], v[24:25], v[146:147], v[46:47] op_sel:[1,0,0] op_sel_hi:[1,1,1]
	v_pk_fma_f32 v[34:35], v[20:21], v[146:147], v[34:35] op_sel:[1,0,0] op_sel_hi:[1,1,1]
	v_pk_fma_f32 v[46:47], v[26:27], v[156:157], v[46:47] op_sel_hi:[0,1,1]
	v_pk_fma_f32 v[34:35], v[22:23], v[156:157], v[34:35] op_sel_hi:[0,1,1]
	v_pk_fma_f32 v[46:47], v[26:27], v[158:159], v[46:47] op_sel:[1,0,0] op_sel_hi:[1,1,1]
	v_pk_fma_f32 v[34:35], v[22:23], v[158:159], v[34:35] op_sel:[1,0,0] op_sel_hi:[1,1,1]
	v_pk_mul_f32 v[20:21], v[20:21], v[168:169]
	v_add_f32_dpp v28, v46, v34 row_half_mirror row_mask:0xf bank_mask:0xf
	v_add_f32_dpp v151, v47, v35 row_half_mirror row_mask:0xf bank_mask:0xf
	v_pk_mul_f32 v[22:23], v[22:23], v[170:171]
	v_add_f32_dpp v28, v28, v28 row_ror:8 row_mask:0xf bank_mask:0xf
	v_pk_mul_f32 v[24:25], v[24:25], v[168:169]
	v_pk_mul_f32 v[26:27], v[26:27], v[170:171]
	v_add_f32_dpp v28, v28, v28 quad_perm:[1,0,3,2] row_mask:0xf bank_mask:0xf
	v_pk_fma_f32 v[20:21], v[180:181], v[8:9], v[20:21] op_sel_hi:[1,0,1]
	v_pk_fma_f32 v[22:23], v[182:183], v[8:9], v[22:23] op_sel_hi:[1,0,1]
	v_add_f32_dpp v28, v28, v28 quad_perm:[2,3,0,1] row_mask:0xf bank_mask:0xf
	v_pk_fma_f32 v[24:25], v[180:181], v[10:11], v[24:25] op_sel_hi:[1,0,1]
	v_pk_fma_f32 v[26:27], v[182:183], v[10:11], v[26:27] op_sel_hi:[1,0,1]
	v_mov_b32_dpp v30, v28 row_half_mirror row_mask:0xf bank_mask:0xf
	v_fmac_f32_e32 v151, 0x3e000000, v9
	v_pk_fma_f32 v[20:21], v[88:89], v[28:29], v[20:21] op_sel_hi:[1,0,1] neg_lo:[0,1,0] neg_hi:[0,1,0]
	v_pk_fma_f32 v[22:23], v[90:91], v[28:29], v[22:23] op_sel_hi:[1,0,1] neg_lo:[0,1,0] neg_hi:[0,1,0]
	v_pk_fma_f32 v[24:25], v[88:89], v[30:31], v[24:25] op_sel_hi:[1,0,1] neg_lo:[0,1,0] neg_hi:[0,1,0]
	v_pk_fma_f32 v[26:27], v[90:91], v[30:31], v[26:27] op_sel_hi:[1,0,1] neg_lo:[0,1,0] neg_hi:[0,1,0]
	ds_read_b128 v[144:147], v195 offset:1280
	ds_read_b128 v[156:159], v195 offset:9472
	ds_read_b128 v[180:183], v195 offset:17664
	ds_read_b128 v[88:91], v195 offset:34048
	ds_read_b64 v[8:9], v196 offset:2560
	ds_read_b32 v10, v36 offset:2560
	s_waitcnt lgkmcnt(6)
	v_pk_mul_f32 v[46:47], v[24:25], v[140:141] op_sel_hi:[0,1]
	v_pk_mul_f32 v[34:35], v[20:21], v[140:141] op_sel_hi:[0,1]
	v_pk_fma_f32 v[46:47], v[24:25], v[142:143], v[46:47] op_sel:[1,0,0] op_sel_hi:[1,1,1]
	v_pk_fma_f32 v[34:35], v[20:21], v[142:143], v[34:35] op_sel:[1,0,0] op_sel_hi:[1,1,1]
	v_pk_fma_f32 v[46:47], v[26:27], v[152:153], v[46:47] op_sel_hi:[0,1,1]
	v_pk_fma_f32 v[34:35], v[22:23], v[152:153], v[34:35] op_sel_hi:[0,1,1]
	v_pk_fma_f32 v[46:47], v[26:27], v[154:155], v[46:47] op_sel:[1,0,0] op_sel_hi:[1,1,1]
	v_pk_fma_f32 v[34:35], v[22:23], v[154:155], v[34:35] op_sel:[1,0,0] op_sel_hi:[1,1,1]
	v_pk_fma_f32 v[20:21], v[176:177], v[4:5], v[20:21] op_sel_hi:[1,0,1]
	v_add_f32_dpp v28, v46, v34 row_half_mirror row_mask:0xf bank_mask:0xf
	v_add_f32_dpp v172, v47, v35 row_half_mirror row_mask:0xf bank_mask:0xf
	v_pk_fma_f32 v[22:23], v[178:179], v[4:5], v[22:23] op_sel_hi:[1,0,1]
	v_add_f32_dpp v28, v28, v28 row_ror:8 row_mask:0xf bank_mask:0xf
	v_pk_fma_f32 v[24:25], v[176:177], v[6:7], v[24:25] op_sel_hi:[1,0,1]
	v_pk_fma_f32 v[26:27], v[178:179], v[6:7], v[26:27] op_sel_hi:[1,0,1]
	v_add_f32_dpp v28, v28, v28 quad_perm:[1,0,3,2] row_mask:0xf bank_mask:0xf
	v_fmac_f32_e32 v172, 0x3e000000, v5
	v_add_f32_dpp v160, v148, v148 row_ror:8 row_mask:0xf bank_mask:0x3
	v_add_f32_dpp v28, v28, v28 quad_perm:[2,3,0,1] row_mask:0xf bank_mask:0xf
	v_pk_fma_f32 v[20:21], v[84:85], v[28:29], v[20:21] op_sel_hi:[1,0,1] neg_lo:[0,1,0] neg_hi:[0,1,0]
	v_pk_fma_f32 v[22:23], v[86:87], v[28:29], v[22:23] op_sel_hi:[1,0,1] neg_lo:[0,1,0] neg_hi:[0,1,0]
	v_mov_b32_dpp v30, v28 row_half_mirror row_mask:0xf bank_mask:0xf
	v_pk_fma_f32 v[24:25], v[84:85], v[30:31], v[24:25] op_sel_hi:[1,0,1] neg_lo:[0,1,0] neg_hi:[0,1,0]
	v_pk_fma_f32 v[26:27], v[86:87], v[30:31], v[26:27] op_sel_hi:[1,0,1] neg_lo:[0,1,0] neg_hi:[0,1,0]
	v_add_f32_dpp v160, v149, v149 row_ror:8 row_mask:0xf bank_mask:0xc
	v_add_f32_dpp v161, v150, v150 row_ror:8 row_mask:0xf bank_mask:0x3
	ds_read_b128 v[140:143], v195 offset:1536
	ds_read_b128 v[152:155], v195 offset:9728
	ds_read_b128 v[176:179], v195 offset:17920
	ds_read_b128 v[84:87], v195 offset:34304
	ds_read_b64 v[4:5], v196 offset:3072
	ds_read_b32 v6, v36 offset:3072
	s_waitcnt lgkmcnt(6)
	v_pk_mul_f32 v[46:47], v[24:25], v[144:145] op_sel_hi:[0,1]
	v_pk_mul_f32 v[34:35], v[20:21], v[144:145] op_sel_hi:[0,1]
	v_pk_fma_f32 v[46:47], v[24:25], v[146:147], v[46:47] op_sel:[1,0,0] op_sel_hi:[1,1,1]
	v_pk_fma_f32 v[34:35], v[20:21], v[146:147], v[34:35] op_sel:[1,0,0] op_sel_hi:[1,1,1]
	v_pk_fma_f32 v[46:47], v[26:27], v[156:157], v[46:47] op_sel_hi:[0,1,1]
	v_pk_fma_f32 v[34:35], v[22:23], v[156:157], v[34:35] op_sel_hi:[0,1,1]
	v_pk_fma_f32 v[46:47], v[26:27], v[158:159], v[46:47] op_sel:[1,0,0] op_sel_hi:[1,1,1]
	v_pk_fma_f32 v[34:35], v[22:23], v[158:159], v[34:35] op_sel:[1,0,0] op_sel_hi:[1,1,1]
	v_pk_fma_f32 v[20:21], v[180:181], v[8:9], v[20:21] op_sel_hi:[1,0,1]
	v_add_f32_dpp v28, v46, v34 row_half_mirror row_mask:0xf bank_mask:0xf
	v_add_f32_dpp v173, v47, v35 row_half_mirror row_mask:0xf bank_mask:0xf
	v_pk_fma_f32 v[22:23], v[182:183], v[8:9], v[22:23] op_sel_hi:[1,0,1]
	v_add_f32_dpp v28, v28, v28 row_ror:8 row_mask:0xf bank_mask:0xf
	v_pk_fma_f32 v[24:25], v[180:181], v[10:11], v[24:25] op_sel_hi:[1,0,1]
	v_pk_fma_f32 v[26:27], v[182:183], v[10:11], v[26:27] op_sel_hi:[1,0,1]
	v_add_f32_dpp v28, v28, v28 quad_perm:[1,0,3,2] row_mask:0xf bank_mask:0xf
	v_fmac_f32_e32 v173, 0x3e000000, v9
	v_add_f32_dpp v161, v151, v151 row_ror:8 row_mask:0xf bank_mask:0xc
	v_add_f32_dpp v28, v28, v28 quad_perm:[2,3,0,1] row_mask:0xf bank_mask:0xf
	v_pk_fma_f32 v[20:21], v[88:89], v[28:29], v[20:21] op_sel_hi:[1,0,1] neg_lo:[0,1,0] neg_hi:[0,1,0]
	v_pk_fma_f32 v[22:23], v[90:91], v[28:29], v[22:23] op_sel_hi:[1,0,1] neg_lo:[0,1,0] neg_hi:[0,1,0]
	v_mov_b32_dpp v30, v28 row_half_mirror row_mask:0xf bank_mask:0xf
	v_pk_fma_f32 v[24:25], v[88:89], v[30:31], v[24:25] op_sel_hi:[1,0,1] neg_lo:[0,1,0] neg_hi:[0,1,0]
	v_pk_fma_f32 v[26:27], v[90:91], v[30:31], v[26:27] op_sel_hi:[1,0,1] neg_lo:[0,1,0] neg_hi:[0,1,0]
	v_add_f32_dpp v160, v160, v160 quad_perm:[1,0,3,2] row_mask:0xf bank_mask:0xf
	v_add_f32_dpp v161, v161, v161 quad_perm:[1,0,3,2] row_mask:0xf bank_mask:0xf
	ds_read_b128 v[144:147], v195 offset:1792
	ds_read_b128 v[156:159], v195 offset:9984
	ds_read_b128 v[168:171], v195 offset:26368
	ds_read_b128 v[180:183], v195 offset:18176
	ds_read_b128 v[88:91], v195 offset:34560
	ds_read_b64 v[8:9], v196 offset:3584
	ds_read_b32 v10, v36 offset:3584
	s_waitcnt lgkmcnt(7)
	v_pk_mul_f32 v[46:47], v[24:25], v[140:141] op_sel_hi:[0,1]
	v_pk_mul_f32 v[34:35], v[20:21], v[140:141] op_sel_hi:[0,1]
	v_pk_fma_f32 v[46:47], v[24:25], v[142:143], v[46:47] op_sel:[1,0,0] op_sel_hi:[1,1,1]
	v_pk_fma_f32 v[34:35], v[20:21], v[142:143], v[34:35] op_sel:[1,0,0] op_sel_hi:[1,1,1]
	v_pk_fma_f32 v[46:47], v[26:27], v[152:153], v[46:47] op_sel_hi:[0,1,1]
	v_pk_fma_f32 v[34:35], v[22:23], v[152:153], v[34:35] op_sel_hi:[0,1,1]
	v_pk_fma_f32 v[46:47], v[26:27], v[154:155], v[46:47] op_sel:[1,0,0] op_sel_hi:[1,1,1]
	v_pk_fma_f32 v[34:35], v[22:23], v[154:155], v[34:35] op_sel:[1,0,0] op_sel_hi:[1,1,1]
	v_pk_fma_f32 v[20:21], v[176:177], v[4:5], v[20:21] op_sel_hi:[1,0,1]
	v_add_f32_dpp v28, v46, v34 row_half_mirror row_mask:0xf bank_mask:0xf
	v_add_f32_dpp v174, v47, v35 row_half_mirror row_mask:0xf bank_mask:0xf
	v_pk_fma_f32 v[22:23], v[178:179], v[4:5], v[22:23] op_sel_hi:[1,0,1]
	v_add_f32_dpp v28, v28, v28 row_ror:8 row_mask:0xf bank_mask:0xf
	v_pk_fma_f32 v[24:25], v[176:177], v[6:7], v[24:25] op_sel_hi:[1,0,1]
	v_pk_fma_f32 v[26:27], v[178:179], v[6:7], v[26:27] op_sel_hi:[1,0,1]
	v_add_f32_dpp v28, v28, v28 quad_perm:[1,0,3,2] row_mask:0xf bank_mask:0xf
	v_fmac_f32_e32 v174, 0x3e000000, v5
	v_add_f32_dpp v160, v160, v160 quad_perm:[2,3,0,1] row_mask:0xf bank_mask:0xf
	v_add_f32_dpp v28, v28, v28 quad_perm:[2,3,0,1] row_mask:0xf bank_mask:0xf
	v_pk_fma_f32 v[20:21], v[84:85], v[28:29], v[20:21] op_sel_hi:[1,0,1] neg_lo:[0,1,0] neg_hi:[0,1,0]
	v_pk_fma_f32 v[22:23], v[86:87], v[28:29], v[22:23] op_sel_hi:[1,0,1] neg_lo:[0,1,0] neg_hi:[0,1,0]
	v_mov_b32_dpp v30, v28 row_half_mirror row_mask:0xf bank_mask:0xf
	v_pk_fma_f32 v[24:25], v[84:85], v[30:31], v[24:25] op_sel_hi:[1,0,1] neg_lo:[0,1,0] neg_hi:[0,1,0]
	v_pk_fma_f32 v[26:27], v[86:87], v[30:31], v[26:27] op_sel_hi:[1,0,1] neg_lo:[0,1,0] neg_hi:[0,1,0]
	v_add_f32_dpp v161, v161, v161 quad_perm:[2,3,0,1] row_mask:0xf bank_mask:0xf
	ds_write_b32 v102, v160 offset:0
	ds_read_b128 v[140:143], v195 offset:2048
	ds_read_b128 v[152:155], v195 offset:10240
	ds_read_b128 v[176:179], v195 offset:18432
	ds_read_b128 v[84:87], v195 offset:34816
	ds_read_b64 v[4:5], v196 offset:4096
	ds_read_b32 v6, v36 offset:4096
	s_waitcnt lgkmcnt(7)
	v_pk_mul_f32 v[46:47], v[24:25], v[144:145] op_sel_hi:[0,1]
	v_pk_mul_f32 v[34:35], v[20:21], v[144:145] op_sel_hi:[0,1]
	v_pk_fma_f32 v[46:47], v[24:25], v[146:147], v[46:47] op_sel:[1,0,0] op_sel_hi:[1,1,1]
	v_pk_fma_f32 v[34:35], v[20:21], v[146:147], v[34:35] op_sel:[1,0,0] op_sel_hi:[1,1,1]
	v_pk_fma_f32 v[46:47], v[26:27], v[156:157], v[46:47] op_sel_hi:[0,1,1]
	v_pk_fma_f32 v[34:35], v[22:23], v[156:157], v[34:35] op_sel_hi:[0,1,1]
	v_pk_fma_f32 v[46:47], v[26:27], v[158:159], v[46:47] op_sel:[1,0,0] op_sel_hi:[1,1,1]
	v_pk_fma_f32 v[34:35], v[22:23], v[158:159], v[34:35] op_sel:[1,0,0] op_sel_hi:[1,1,1]
	v_pk_mul_f32 v[20:21], v[20:21], v[168:169]
	v_add_f32_dpp v28, v46, v34 row_half_mirror row_mask:0xf bank_mask:0xf
	v_add_f32_dpp v175, v47, v35 row_half_mirror row_mask:0xf bank_mask:0xf
	v_pk_mul_f32 v[22:23], v[22:23], v[170:171]
	v_add_f32_dpp v28, v28, v28 row_ror:8 row_mask:0xf bank_mask:0xf
	v_pk_mul_f32 v[24:25], v[24:25], v[168:169]
	v_pk_mul_f32 v[26:27], v[26:27], v[170:171]
	v_add_f32_dpp v28, v28, v28 quad_perm:[1,0,3,2] row_mask:0xf bank_mask:0xf
	v_pk_fma_f32 v[20:21], v[180:181], v[8:9], v[20:21] op_sel_hi:[1,0,1]
	v_pk_fma_f32 v[22:23], v[182:183], v[8:9], v[22:23] op_sel_hi:[1,0,1]
	v_add_f32_dpp v28, v28, v28 quad_perm:[2,3,0,1] row_mask:0xf bank_mask:0xf
	v_pk_fma_f32 v[24:25], v[180:181], v[10:11], v[24:25] op_sel_hi:[1,0,1]
	v_pk_fma_f32 v[26:27], v[182:183], v[10:11], v[26:27] op_sel_hi:[1,0,1]
	v_mov_b32_dpp v30, v28 row_half_mirror row_mask:0xf bank_mask:0xf
	v_fmac_f32_e32 v175, 0x3e000000, v9
	v_pk_fma_f32 v[20:21], v[88:89], v[28:29], v[20:21] op_sel_hi:[1,0,1] neg_lo:[0,1,0] neg_hi:[0,1,0]
	v_pk_fma_f32 v[22:23], v[90:91], v[28:29], v[22:23] op_sel_hi:[1,0,1] neg_lo:[0,1,0] neg_hi:[0,1,0]
	v_pk_fma_f32 v[24:25], v[88:89], v[30:31], v[24:25] op_sel_hi:[1,0,1] neg_lo:[0,1,0] neg_hi:[0,1,0]
	v_pk_fma_f32 v[26:27], v[90:91], v[30:31], v[26:27] op_sel_hi:[1,0,1] neg_lo:[0,1,0] neg_hi:[0,1,0]
	ds_write_b32 v102, v161 offset:256
	ds_read_b128 v[144:147], v195 offset:2304
	ds_read_b128 v[156:159], v195 offset:10496
	ds_read_b128 v[180:183], v195 offset:18688
	ds_read_b128 v[88:91], v195 offset:35072
	ds_read_b64 v[8:9], v196 offset:4608
	ds_read_b32 v10, v36 offset:4608
	s_waitcnt lgkmcnt(7)
	v_pk_mul_f32 v[46:47], v[24:25], v[140:141] op_sel_hi:[0,1]
	v_pk_mul_f32 v[34:35], v[20:21], v[140:141] op_sel_hi:[0,1]
	v_pk_fma_f32 v[46:47], v[24:25], v[142:143], v[46:47] op_sel:[1,0,0] op_sel_hi:[1,1,1]
	v_pk_fma_f32 v[34:35], v[20:21], v[142:143], v[34:35] op_sel:[1,0,0] op_sel_hi:[1,1,1]
	v_pk_fma_f32 v[46:47], v[26:27], v[152:153], v[46:47] op_sel_hi:[0,1,1]
	v_pk_fma_f32 v[34:35], v[22:23], v[152:153], v[34:35] op_sel_hi:[0,1,1]
	v_pk_fma_f32 v[46:47], v[26:27], v[154:155], v[46:47] op_sel:[1,0,0] op_sel_hi:[1,1,1]
	v_pk_fma_f32 v[34:35], v[22:23], v[154:155], v[34:35] op_sel:[1,0,0] op_sel_hi:[1,1,1]
	v_pk_fma_f32 v[20:21], v[176:177], v[4:5], v[20:21] op_sel_hi:[1,0,1]
	v_add_f32_dpp v28, v46, v34 row_half_mirror row_mask:0xf bank_mask:0xf
	v_add_f32_dpp v148, v47, v35 row_half_mirror row_mask:0xf bank_mask:0xf
	v_pk_fma_f32 v[22:23], v[178:179], v[4:5], v[22:23] op_sel_hi:[1,0,1]
	v_add_f32_dpp v28, v28, v28 row_ror:8 row_mask:0xf bank_mask:0xf
	v_pk_fma_f32 v[24:25], v[176:177], v[6:7], v[24:25] op_sel_hi:[1,0,1]
	v_pk_fma_f32 v[26:27], v[178:179], v[6:7], v[26:27] op_sel_hi:[1,0,1]
	v_add_f32_dpp v28, v28, v28 quad_perm:[1,0,3,2] row_mask:0xf bank_mask:0xf
	v_fmac_f32_e32 v148, 0x3e000000, v5
	v_add_f32_dpp v162, v172, v172 row_ror:8 row_mask:0xf bank_mask:0x3
	v_add_f32_dpp v28, v28, v28 quad_perm:[2,3,0,1] row_mask:0xf bank_mask:0xf
	v_pk_fma_f32 v[20:21], v[84:85], v[28:29], v[20:21] op_sel_hi:[1,0,1] neg_lo:[0,1,0] neg_hi:[0,1,0]
	v_pk_fma_f32 v[22:23], v[86:87], v[28:29], v[22:23] op_sel_hi:[1,0,1] neg_lo:[0,1,0] neg_hi:[0,1,0]
	v_mov_b32_dpp v30, v28 row_half_mirror row_mask:0xf bank_mask:0xf
	v_pk_fma_f32 v[24:25], v[84:85], v[30:31], v[24:25] op_sel_hi:[1,0,1] neg_lo:[0,1,0] neg_hi:[0,1,0]
	v_pk_fma_f32 v[26:27], v[86:87], v[30:31], v[26:27] op_sel_hi:[1,0,1] neg_lo:[0,1,0] neg_hi:[0,1,0]
	v_add_f32_dpp v162, v173, v173 row_ror:8 row_mask:0xf bank_mask:0xc
	v_add_f32_dpp v163, v174, v174 row_ror:8 row_mask:0xf bank_mask:0x3
	ds_read_b128 v[140:143], v195 offset:2560
	ds_read_b128 v[152:155], v195 offset:10752
	ds_read_b128 v[176:179], v195 offset:18944
	ds_read_b128 v[84:87], v195 offset:35328
	ds_read_b64 v[4:5], v196 offset:5120
	ds_read_b32 v6, v36 offset:5120
	s_waitcnt lgkmcnt(6)
	v_pk_mul_f32 v[46:47], v[24:25], v[144:145] op_sel_hi:[0,1]
	v_pk_mul_f32 v[34:35], v[20:21], v[144:145] op_sel_hi:[0,1]
	v_pk_fma_f32 v[46:47], v[24:25], v[146:147], v[46:47] op_sel:[1,0,0] op_sel_hi:[1,1,1]
	v_pk_fma_f32 v[34:35], v[20:21], v[146:147], v[34:35] op_sel:[1,0,0] op_sel_hi:[1,1,1]
	v_pk_fma_f32 v[46:47], v[26:27], v[156:157], v[46:47] op_sel_hi:[0,1,1]
	v_pk_fma_f32 v[34:35], v[22:23], v[156:157], v[34:35] op_sel_hi:[0,1,1]
	v_pk_fma_f32 v[46:47], v[26:27], v[158:159], v[46:47] op_sel:[1,0,0] op_sel_hi:[1,1,1]
	v_pk_fma_f32 v[34:35], v[22:23], v[158:159], v[34:35] op_sel:[1,0,0] op_sel_hi:[1,1,1]
	v_pk_fma_f32 v[20:21], v[180:181], v[8:9], v[20:21] op_sel_hi:[1,0,1]
	v_add_f32_dpp v28, v46, v34 row_half_mirror row_mask:0xf bank_mask:0xf
	v_add_f32_dpp v149, v47, v35 row_half_mirror row_mask:0xf bank_mask:0xf
	v_pk_fma_f32 v[22:23], v[182:183], v[8:9], v[22:23] op_sel_hi:[1,0,1]
	v_add_f32_dpp v28, v28, v28 row_ror:8 row_mask:0xf bank_mask:0xf
	v_pk_fma_f32 v[24:25], v[180:181], v[10:11], v[24:25] op_sel_hi:[1,0,1]
	v_pk_fma_f32 v[26:27], v[182:183], v[10:11], v[26:27] op_sel_hi:[1,0,1]
	v_add_f32_dpp v28, v28, v28 quad_perm:[1,0,3,2] row_mask:0xf bank_mask:0xf
	v_fmac_f32_e32 v149, 0x3e000000, v9
	v_add_f32_dpp v163, v175, v175 row_ror:8 row_mask:0xf bank_mask:0xc
	v_add_f32_dpp v28, v28, v28 quad_perm:[2,3,0,1] row_mask:0xf bank_mask:0xf
	v_pk_fma_f32 v[20:21], v[88:89], v[28:29], v[20:21] op_sel_hi:[1,0,1] neg_lo:[0,1,0] neg_hi:[0,1,0]
	v_pk_fma_f32 v[22:23], v[90:91], v[28:29], v[22:23] op_sel_hi:[1,0,1] neg_lo:[0,1,0] neg_hi:[0,1,0]
	v_mov_b32_dpp v30, v28 row_half_mirror row_mask:0xf bank_mask:0xf
	v_pk_fma_f32 v[24:25], v[88:89], v[30:31], v[24:25] op_sel_hi:[1,0,1] neg_lo:[0,1,0] neg_hi:[0,1,0]
	v_pk_fma_f32 v[26:27], v[90:91], v[30:31], v[26:27] op_sel_hi:[1,0,1] neg_lo:[0,1,0] neg_hi:[0,1,0]
	v_add_f32_dpp v162, v162, v162 quad_perm:[1,0,3,2] row_mask:0xf bank_mask:0xf
	v_add_f32_dpp v163, v163, v163 quad_perm:[1,0,3,2] row_mask:0xf bank_mask:0xf
	ds_read_b128 v[144:147], v195 offset:2816
	ds_read_b128 v[156:159], v195 offset:11008
	ds_read_b128 v[168:171], v195 offset:27392
	ds_read_b128 v[180:183], v195 offset:19200
	ds_read_b128 v[88:91], v195 offset:35584
	ds_read_b64 v[8:9], v196 offset:5632
	ds_read_b32 v10, v36 offset:5632
	s_waitcnt lgkmcnt(7)
	v_pk_mul_f32 v[46:47], v[24:25], v[140:141] op_sel_hi:[0,1]
	v_pk_mul_f32 v[34:35], v[20:21], v[140:141] op_sel_hi:[0,1]
	v_pk_fma_f32 v[46:47], v[24:25], v[142:143], v[46:47] op_sel:[1,0,0] op_sel_hi:[1,1,1]
	v_pk_fma_f32 v[34:35], v[20:21], v[142:143], v[34:35] op_sel:[1,0,0] op_sel_hi:[1,1,1]
	v_pk_fma_f32 v[46:47], v[26:27], v[152:153], v[46:47] op_sel_hi:[0,1,1]
	v_pk_fma_f32 v[34:35], v[22:23], v[152:153], v[34:35] op_sel_hi:[0,1,1]
	v_pk_fma_f32 v[46:47], v[26:27], v[154:155], v[46:47] op_sel:[1,0,0] op_sel_hi:[1,1,1]
	v_pk_fma_f32 v[34:35], v[22:23], v[154:155], v[34:35] op_sel:[1,0,0] op_sel_hi:[1,1,1]
	v_pk_fma_f32 v[20:21], v[176:177], v[4:5], v[20:21] op_sel_hi:[1,0,1]
	v_add_f32_dpp v28, v46, v34 row_half_mirror row_mask:0xf bank_mask:0xf
	v_add_f32_dpp v150, v47, v35 row_half_mirror row_mask:0xf bank_mask:0xf
	v_pk_fma_f32 v[22:23], v[178:179], v[4:5], v[22:23] op_sel_hi:[1,0,1]
	v_add_f32_dpp v28, v28, v28 row_ror:8 row_mask:0xf bank_mask:0xf
	v_pk_fma_f32 v[24:25], v[176:177], v[6:7], v[24:25] op_sel_hi:[1,0,1]
	v_pk_fma_f32 v[26:27], v[178:179], v[6:7], v[26:27] op_sel_hi:[1,0,1]
	v_add_f32_dpp v28, v28, v28 quad_perm:[1,0,3,2] row_mask:0xf bank_mask:0xf
	v_fmac_f32_e32 v150, 0x3e000000, v5
	v_add_f32_dpp v162, v162, v162 quad_perm:[2,3,0,1] row_mask:0xf bank_mask:0xf
	v_add_f32_dpp v28, v28, v28 quad_perm:[2,3,0,1] row_mask:0xf bank_mask:0xf
	v_pk_fma_f32 v[20:21], v[84:85], v[28:29], v[20:21] op_sel_hi:[1,0,1] neg_lo:[0,1,0] neg_hi:[0,1,0]
	v_pk_fma_f32 v[22:23], v[86:87], v[28:29], v[22:23] op_sel_hi:[1,0,1] neg_lo:[0,1,0] neg_hi:[0,1,0]
	v_mov_b32_dpp v30, v28 row_half_mirror row_mask:0xf bank_mask:0xf
	v_pk_fma_f32 v[24:25], v[84:85], v[30:31], v[24:25] op_sel_hi:[1,0,1] neg_lo:[0,1,0] neg_hi:[0,1,0]
	v_pk_fma_f32 v[26:27], v[86:87], v[30:31], v[26:27] op_sel_hi:[1,0,1] neg_lo:[0,1,0] neg_hi:[0,1,0]
	v_add_f32_dpp v163, v163, v163 quad_perm:[2,3,0,1] row_mask:0xf bank_mask:0xf
	ds_write_b32 v102, v162 offset:512
	ds_read_b128 v[140:143], v195 offset:3072
	ds_read_b128 v[152:155], v195 offset:11264
	ds_read_b128 v[176:179], v195 offset:19456
	ds_read_b128 v[84:87], v195 offset:35840
	ds_read_b64 v[4:5], v196 offset:6144
	ds_read_b32 v6, v36 offset:6144
	s_waitcnt lgkmcnt(7)
	v_pk_mul_f32 v[46:47], v[24:25], v[144:145] op_sel_hi:[0,1]
	v_pk_mul_f32 v[34:35], v[20:21], v[144:145] op_sel_hi:[0,1]
	v_pk_fma_f32 v[46:47], v[24:25], v[146:147], v[46:47] op_sel:[1,0,0] op_sel_hi:[1,1,1]
	v_pk_fma_f32 v[34:35], v[20:21], v[146:147], v[34:35] op_sel:[1,0,0] op_sel_hi:[1,1,1]
	v_pk_fma_f32 v[46:47], v[26:27], v[156:157], v[46:47] op_sel_hi:[0,1,1]
	v_pk_fma_f32 v[34:35], v[22:23], v[156:157], v[34:35] op_sel_hi:[0,1,1]
	v_pk_fma_f32 v[46:47], v[26:27], v[158:159], v[46:47] op_sel:[1,0,0] op_sel_hi:[1,1,1]
	v_pk_fma_f32 v[34:35], v[22:23], v[158:159], v[34:35] op_sel:[1,0,0] op_sel_hi:[1,1,1]
	v_pk_mul_f32 v[20:21], v[20:21], v[168:169]
	v_add_f32_dpp v28, v46, v34 row_half_mirror row_mask:0xf bank_mask:0xf
	v_add_f32_dpp v151, v47, v35 row_half_mirror row_mask:0xf bank_mask:0xf
	v_pk_mul_f32 v[22:23], v[22:23], v[170:171]
	v_add_f32_dpp v28, v28, v28 row_ror:8 row_mask:0xf bank_mask:0xf
	v_pk_mul_f32 v[24:25], v[24:25], v[168:169]
	v_pk_mul_f32 v[26:27], v[26:27], v[170:171]
	v_add_f32_dpp v28, v28, v28 quad_perm:[1,0,3,2] row_mask:0xf bank_mask:0xf
	v_pk_fma_f32 v[20:21], v[180:181], v[8:9], v[20:21] op_sel_hi:[1,0,1]
	v_pk_fma_f32 v[22:23], v[182:183], v[8:9], v[22:23] op_sel_hi:[1,0,1]
	v_add_f32_dpp v28, v28, v28 quad_perm:[2,3,0,1] row_mask:0xf bank_mask:0xf
	v_pk_fma_f32 v[24:25], v[180:181], v[10:11], v[24:25] op_sel_hi:[1,0,1]
	v_pk_fma_f32 v[26:27], v[182:183], v[10:11], v[26:27] op_sel_hi:[1,0,1]
	v_mov_b32_dpp v30, v28 row_half_mirror row_mask:0xf bank_mask:0xf
	v_fmac_f32_e32 v151, 0x3e000000, v9
	v_pk_fma_f32 v[20:21], v[88:89], v[28:29], v[20:21] op_sel_hi:[1,0,1] neg_lo:[0,1,0] neg_hi:[0,1,0]
	v_pk_fma_f32 v[22:23], v[90:91], v[28:29], v[22:23] op_sel_hi:[1,0,1] neg_lo:[0,1,0] neg_hi:[0,1,0]
	v_pk_fma_f32 v[24:25], v[88:89], v[30:31], v[24:25] op_sel_hi:[1,0,1] neg_lo:[0,1,0] neg_hi:[0,1,0]
	v_pk_fma_f32 v[26:27], v[90:91], v[30:31], v[26:27] op_sel_hi:[1,0,1] neg_lo:[0,1,0] neg_hi:[0,1,0]
	ds_write_b32 v102, v163 offset:768
	ds_read_b128 v[144:147], v195 offset:3328
	ds_read_b128 v[156:159], v195 offset:11520
	ds_read_b128 v[180:183], v195 offset:19712
	ds_read_b128 v[88:91], v195 offset:36096
	ds_read_b64 v[8:9], v196 offset:6656
	ds_read_b32 v10, v36 offset:6656
	s_waitcnt lgkmcnt(7)
	v_pk_mul_f32 v[46:47], v[24:25], v[140:141] op_sel_hi:[0,1]
	v_pk_mul_f32 v[34:35], v[20:21], v[140:141] op_sel_hi:[0,1]
	v_pk_fma_f32 v[46:47], v[24:25], v[142:143], v[46:47] op_sel:[1,0,0] op_sel_hi:[1,1,1]
	v_pk_fma_f32 v[34:35], v[20:21], v[142:143], v[34:35] op_sel:[1,0,0] op_sel_hi:[1,1,1]
	v_pk_fma_f32 v[46:47], v[26:27], v[152:153], v[46:47] op_sel_hi:[0,1,1]
	v_pk_fma_f32 v[34:35], v[22:23], v[152:153], v[34:35] op_sel_hi:[0,1,1]
	v_pk_fma_f32 v[46:47], v[26:27], v[154:155], v[46:47] op_sel:[1,0,0] op_sel_hi:[1,1,1]
	v_pk_fma_f32 v[34:35], v[22:23], v[154:155], v[34:35] op_sel:[1,0,0] op_sel_hi:[1,1,1]
	v_pk_fma_f32 v[20:21], v[176:177], v[4:5], v[20:21] op_sel_hi:[1,0,1]
	v_add_f32_dpp v28, v46, v34 row_half_mirror row_mask:0xf bank_mask:0xf
	v_add_f32_dpp v172, v47, v35 row_half_mirror row_mask:0xf bank_mask:0xf
	v_pk_fma_f32 v[22:23], v[178:179], v[4:5], v[22:23] op_sel_hi:[1,0,1]
	v_add_f32_dpp v28, v28, v28 row_ror:8 row_mask:0xf bank_mask:0xf
	v_pk_fma_f32 v[24:25], v[176:177], v[6:7], v[24:25] op_sel_hi:[1,0,1]
	v_pk_fma_f32 v[26:27], v[178:179], v[6:7], v[26:27] op_sel_hi:[1,0,1]
	v_add_f32_dpp v28, v28, v28 quad_perm:[1,0,3,2] row_mask:0xf bank_mask:0xf
	v_fmac_f32_e32 v172, 0x3e000000, v5
	v_add_f32_dpp v160, v148, v148 row_ror:8 row_mask:0xf bank_mask:0x3
	v_add_f32_dpp v28, v28, v28 quad_perm:[2,3,0,1] row_mask:0xf bank_mask:0xf
	v_pk_fma_f32 v[20:21], v[84:85], v[28:29], v[20:21] op_sel_hi:[1,0,1] neg_lo:[0,1,0] neg_hi:[0,1,0]
	v_pk_fma_f32 v[22:23], v[86:87], v[28:29], v[22:23] op_sel_hi:[1,0,1] neg_lo:[0,1,0] neg_hi:[0,1,0]
	v_mov_b32_dpp v30, v28 row_half_mirror row_mask:0xf bank_mask:0xf
	v_pk_fma_f32 v[24:25], v[84:85], v[30:31], v[24:25] op_sel_hi:[1,0,1] neg_lo:[0,1,0] neg_hi:[0,1,0]
	v_pk_fma_f32 v[26:27], v[86:87], v[30:31], v[26:27] op_sel_hi:[1,0,1] neg_lo:[0,1,0] neg_hi:[0,1,0]
	v_add_f32_dpp v160, v149, v149 row_ror:8 row_mask:0xf bank_mask:0xc
	v_add_f32_dpp v161, v150, v150 row_ror:8 row_mask:0xf bank_mask:0x3
	ds_read_b128 v[140:143], v195 offset:3584
	ds_read_b128 v[152:155], v195 offset:11776
	ds_read_b128 v[176:179], v195 offset:19968
	ds_read_b128 v[84:87], v195 offset:36352
	ds_read_b64 v[4:5], v196 offset:7168
	ds_read_b32 v6, v36 offset:7168
	s_waitcnt lgkmcnt(6)
	v_pk_mul_f32 v[46:47], v[24:25], v[144:145] op_sel_hi:[0,1]
	v_pk_mul_f32 v[34:35], v[20:21], v[144:145] op_sel_hi:[0,1]
	v_pk_fma_f32 v[46:47], v[24:25], v[146:147], v[46:47] op_sel:[1,0,0] op_sel_hi:[1,1,1]
	v_pk_fma_f32 v[34:35], v[20:21], v[146:147], v[34:35] op_sel:[1,0,0] op_sel_hi:[1,1,1]
	v_pk_fma_f32 v[46:47], v[26:27], v[156:157], v[46:47] op_sel_hi:[0,1,1]
	v_pk_fma_f32 v[34:35], v[22:23], v[156:157], v[34:35] op_sel_hi:[0,1,1]
	v_pk_fma_f32 v[46:47], v[26:27], v[158:159], v[46:47] op_sel:[1,0,0] op_sel_hi:[1,1,1]
	v_pk_fma_f32 v[34:35], v[22:23], v[158:159], v[34:35] op_sel:[1,0,0] op_sel_hi:[1,1,1]
	v_pk_fma_f32 v[20:21], v[180:181], v[8:9], v[20:21] op_sel_hi:[1,0,1]
	v_add_f32_dpp v28, v46, v34 row_half_mirror row_mask:0xf bank_mask:0xf
	v_add_f32_dpp v173, v47, v35 row_half_mirror row_mask:0xf bank_mask:0xf
	v_pk_fma_f32 v[22:23], v[182:183], v[8:9], v[22:23] op_sel_hi:[1,0,1]
	v_add_f32_dpp v28, v28, v28 row_ror:8 row_mask:0xf bank_mask:0xf
	v_pk_fma_f32 v[24:25], v[180:181], v[10:11], v[24:25] op_sel_hi:[1,0,1]
	v_pk_fma_f32 v[26:27], v[182:183], v[10:11], v[26:27] op_sel_hi:[1,0,1]
	v_add_f32_dpp v28, v28, v28 quad_perm:[1,0,3,2] row_mask:0xf bank_mask:0xf
	v_fmac_f32_e32 v173, 0x3e000000, v9
	v_add_f32_dpp v161, v151, v151 row_ror:8 row_mask:0xf bank_mask:0xc
	v_add_f32_dpp v28, v28, v28 quad_perm:[2,3,0,1] row_mask:0xf bank_mask:0xf
	v_pk_fma_f32 v[20:21], v[88:89], v[28:29], v[20:21] op_sel_hi:[1,0,1] neg_lo:[0,1,0] neg_hi:[0,1,0]
	v_pk_fma_f32 v[22:23], v[90:91], v[28:29], v[22:23] op_sel_hi:[1,0,1] neg_lo:[0,1,0] neg_hi:[0,1,0]
	v_mov_b32_dpp v30, v28 row_half_mirror row_mask:0xf bank_mask:0xf
	v_pk_fma_f32 v[24:25], v[88:89], v[30:31], v[24:25] op_sel_hi:[1,0,1] neg_lo:[0,1,0] neg_hi:[0,1,0]
	v_pk_fma_f32 v[26:27], v[90:91], v[30:31], v[26:27] op_sel_hi:[1,0,1] neg_lo:[0,1,0] neg_hi:[0,1,0]
	v_add_f32_dpp v160, v160, v160 quad_perm:[1,0,3,2] row_mask:0xf bank_mask:0xf
	v_add_f32_dpp v161, v161, v161 quad_perm:[1,0,3,2] row_mask:0xf bank_mask:0xf
	ds_read_b128 v[144:147], v195 offset:3840
	ds_read_b128 v[156:159], v195 offset:12032
	ds_read_b128 v[168:171], v195 offset:28416
	ds_read_b128 v[180:183], v195 offset:20224
	ds_read_b128 v[88:91], v195 offset:36608
	ds_read_b64 v[8:9], v196 offset:7680
	ds_read_b32 v10, v36 offset:7680
	s_waitcnt lgkmcnt(7)
	v_pk_mul_f32 v[46:47], v[24:25], v[140:141] op_sel_hi:[0,1]
	v_pk_mul_f32 v[34:35], v[20:21], v[140:141] op_sel_hi:[0,1]
	v_pk_fma_f32 v[46:47], v[24:25], v[142:143], v[46:47] op_sel:[1,0,0] op_sel_hi:[1,1,1]
	v_pk_fma_f32 v[34:35], v[20:21], v[142:143], v[34:35] op_sel:[1,0,0] op_sel_hi:[1,1,1]
	v_pk_fma_f32 v[46:47], v[26:27], v[152:153], v[46:47] op_sel_hi:[0,1,1]
	v_pk_fma_f32 v[34:35], v[22:23], v[152:153], v[34:35] op_sel_hi:[0,1,1]
	v_pk_fma_f32 v[46:47], v[26:27], v[154:155], v[46:47] op_sel:[1,0,0] op_sel_hi:[1,1,1]
	v_pk_fma_f32 v[34:35], v[22:23], v[154:155], v[34:35] op_sel:[1,0,0] op_sel_hi:[1,1,1]
	v_pk_fma_f32 v[20:21], v[176:177], v[4:5], v[20:21] op_sel_hi:[1,0,1]
	v_add_f32_dpp v28, v46, v34 row_half_mirror row_mask:0xf bank_mask:0xf
	v_add_f32_dpp v174, v47, v35 row_half_mirror row_mask:0xf bank_mask:0xf
	v_pk_fma_f32 v[22:23], v[178:179], v[4:5], v[22:23] op_sel_hi:[1,0,1]
	v_add_f32_dpp v28, v28, v28 row_ror:8 row_mask:0xf bank_mask:0xf
	v_pk_fma_f32 v[24:25], v[176:177], v[6:7], v[24:25] op_sel_hi:[1,0,1]
	v_pk_fma_f32 v[26:27], v[178:179], v[6:7], v[26:27] op_sel_hi:[1,0,1]
	v_add_f32_dpp v28, v28, v28 quad_perm:[1,0,3,2] row_mask:0xf bank_mask:0xf
	v_fmac_f32_e32 v174, 0x3e000000, v5
	v_add_f32_dpp v160, v160, v160 quad_perm:[2,3,0,1] row_mask:0xf bank_mask:0xf
	v_add_f32_dpp v28, v28, v28 quad_perm:[2,3,0,1] row_mask:0xf bank_mask:0xf
	v_pk_fma_f32 v[20:21], v[84:85], v[28:29], v[20:21] op_sel_hi:[1,0,1] neg_lo:[0,1,0] neg_hi:[0,1,0]
	v_pk_fma_f32 v[22:23], v[86:87], v[28:29], v[22:23] op_sel_hi:[1,0,1] neg_lo:[0,1,0] neg_hi:[0,1,0]
	v_mov_b32_dpp v30, v28 row_half_mirror row_mask:0xf bank_mask:0xf
	v_pk_fma_f32 v[24:25], v[84:85], v[30:31], v[24:25] op_sel_hi:[1,0,1] neg_lo:[0,1,0] neg_hi:[0,1,0]
	v_pk_fma_f32 v[26:27], v[86:87], v[30:31], v[26:27] op_sel_hi:[1,0,1] neg_lo:[0,1,0] neg_hi:[0,1,0]
	v_add_f32_dpp v161, v161, v161 quad_perm:[2,3,0,1] row_mask:0xf bank_mask:0xf
	ds_write_b32 v102, v160 offset:1024
	ds_read_b128 v[140:143], v195 offset:4096
	ds_read_b128 v[152:155], v195 offset:12288
	ds_read_b128 v[176:179], v195 offset:20480
	ds_read_b128 v[84:87], v195 offset:36864
	ds_read_b64 v[4:5], v196 offset:8192
	ds_read_b32 v6, v36 offset:8192
	s_waitcnt lgkmcnt(7)
	v_pk_mul_f32 v[46:47], v[24:25], v[144:145] op_sel_hi:[0,1]
	v_pk_mul_f32 v[34:35], v[20:21], v[144:145] op_sel_hi:[0,1]
	v_pk_fma_f32 v[46:47], v[24:25], v[146:147], v[46:47] op_sel:[1,0,0] op_sel_hi:[1,1,1]
	v_pk_fma_f32 v[34:35], v[20:21], v[146:147], v[34:35] op_sel:[1,0,0] op_sel_hi:[1,1,1]
	v_pk_fma_f32 v[46:47], v[26:27], v[156:157], v[46:47] op_sel_hi:[0,1,1]
	v_pk_fma_f32 v[34:35], v[22:23], v[156:157], v[34:35] op_sel_hi:[0,1,1]
	v_pk_fma_f32 v[46:47], v[26:27], v[158:159], v[46:47] op_sel:[1,0,0] op_sel_hi:[1,1,1]
	v_pk_fma_f32 v[34:35], v[22:23], v[158:159], v[34:35] op_sel:[1,0,0] op_sel_hi:[1,1,1]
	v_pk_mul_f32 v[20:21], v[20:21], v[168:169]
	v_add_f32_dpp v28, v46, v34 row_half_mirror row_mask:0xf bank_mask:0xf
	v_add_f32_dpp v175, v47, v35 row_half_mirror row_mask:0xf bank_mask:0xf
	v_pk_mul_f32 v[22:23], v[22:23], v[170:171]
	v_add_f32_dpp v28, v28, v28 row_ror:8 row_mask:0xf bank_mask:0xf
	v_pk_mul_f32 v[24:25], v[24:25], v[168:169]
	v_pk_mul_f32 v[26:27], v[26:27], v[170:171]
	v_add_f32_dpp v28, v28, v28 quad_perm:[1,0,3,2] row_mask:0xf bank_mask:0xf
	v_pk_fma_f32 v[20:21], v[180:181], v[8:9], v[20:21] op_sel_hi:[1,0,1]
	v_pk_fma_f32 v[22:23], v[182:183], v[8:9], v[22:23] op_sel_hi:[1,0,1]
	v_add_f32_dpp v28, v28, v28 quad_perm:[2,3,0,1] row_mask:0xf bank_mask:0xf
	v_pk_fma_f32 v[24:25], v[180:181], v[10:11], v[24:25] op_sel_hi:[1,0,1]
	v_pk_fma_f32 v[26:27], v[182:183], v[10:11], v[26:27] op_sel_hi:[1,0,1]
	v_mov_b32_dpp v30, v28 row_half_mirror row_mask:0xf bank_mask:0xf
	v_fmac_f32_e32 v175, 0x3e000000, v9
	v_pk_fma_f32 v[20:21], v[88:89], v[28:29], v[20:21] op_sel_hi:[1,0,1] neg_lo:[0,1,0] neg_hi:[0,1,0]
	v_pk_fma_f32 v[22:23], v[90:91], v[28:29], v[22:23] op_sel_hi:[1,0,1] neg_lo:[0,1,0] neg_hi:[0,1,0]
	v_pk_fma_f32 v[24:25], v[88:89], v[30:31], v[24:25] op_sel_hi:[1,0,1] neg_lo:[0,1,0] neg_hi:[0,1,0]
	v_pk_fma_f32 v[26:27], v[90:91], v[30:31], v[26:27] op_sel_hi:[1,0,1] neg_lo:[0,1,0] neg_hi:[0,1,0]
	ds_write_b32 v102, v161 offset:1280
	ds_read_b128 v[144:147], v195 offset:4352
	ds_read_b128 v[156:159], v195 offset:12544
	ds_read_b128 v[180:183], v195 offset:20736
	ds_read_b128 v[88:91], v195 offset:37120
	ds_read_b64 v[8:9], v196 offset:8704
	ds_read_b32 v10, v36 offset:8704
	s_waitcnt lgkmcnt(7)
	v_pk_mul_f32 v[46:47], v[24:25], v[140:141] op_sel_hi:[0,1]
	v_pk_mul_f32 v[34:35], v[20:21], v[140:141] op_sel_hi:[0,1]
	v_pk_fma_f32 v[46:47], v[24:25], v[142:143], v[46:47] op_sel:[1,0,0] op_sel_hi:[1,1,1]
	v_pk_fma_f32 v[34:35], v[20:21], v[142:143], v[34:35] op_sel:[1,0,0] op_sel_hi:[1,1,1]
	v_pk_fma_f32 v[46:47], v[26:27], v[152:153], v[46:47] op_sel_hi:[0,1,1]
	v_pk_fma_f32 v[34:35], v[22:23], v[152:153], v[34:35] op_sel_hi:[0,1,1]
	v_pk_fma_f32 v[46:47], v[26:27], v[154:155], v[46:47] op_sel:[1,0,0] op_sel_hi:[1,1,1]
	v_pk_fma_f32 v[34:35], v[22:23], v[154:155], v[34:35] op_sel:[1,0,0] op_sel_hi:[1,1,1]
	v_pk_fma_f32 v[20:21], v[176:177], v[4:5], v[20:21] op_sel_hi:[1,0,1]
	v_add_f32_dpp v28, v46, v34 row_half_mirror row_mask:0xf bank_mask:0xf
	v_add_f32_dpp v148, v47, v35 row_half_mirror row_mask:0xf bank_mask:0xf
	v_pk_fma_f32 v[22:23], v[178:179], v[4:5], v[22:23] op_sel_hi:[1,0,1]
	v_add_f32_dpp v28, v28, v28 row_ror:8 row_mask:0xf bank_mask:0xf
	v_pk_fma_f32 v[24:25], v[176:177], v[6:7], v[24:25] op_sel_hi:[1,0,1]
	v_pk_fma_f32 v[26:27], v[178:179], v[6:7], v[26:27] op_sel_hi:[1,0,1]
	v_add_f32_dpp v28, v28, v28 quad_perm:[1,0,3,2] row_mask:0xf bank_mask:0xf
	v_fmac_f32_e32 v148, 0x3e000000, v5
	v_add_f32_dpp v162, v172, v172 row_ror:8 row_mask:0xf bank_mask:0x3
	v_add_f32_dpp v28, v28, v28 quad_perm:[2,3,0,1] row_mask:0xf bank_mask:0xf
	v_pk_fma_f32 v[20:21], v[84:85], v[28:29], v[20:21] op_sel_hi:[1,0,1] neg_lo:[0,1,0] neg_hi:[0,1,0]
	v_pk_fma_f32 v[22:23], v[86:87], v[28:29], v[22:23] op_sel_hi:[1,0,1] neg_lo:[0,1,0] neg_hi:[0,1,0]
	v_mov_b32_dpp v30, v28 row_half_mirror row_mask:0xf bank_mask:0xf
	v_pk_fma_f32 v[24:25], v[84:85], v[30:31], v[24:25] op_sel_hi:[1,0,1] neg_lo:[0,1,0] neg_hi:[0,1,0]
	v_pk_fma_f32 v[26:27], v[86:87], v[30:31], v[26:27] op_sel_hi:[1,0,1] neg_lo:[0,1,0] neg_hi:[0,1,0]
	v_add_f32_dpp v162, v173, v173 row_ror:8 row_mask:0xf bank_mask:0xc
	v_add_f32_dpp v163, v174, v174 row_ror:8 row_mask:0xf bank_mask:0x3
	ds_read_b128 v[140:143], v195 offset:4608
	ds_read_b128 v[152:155], v195 offset:12800
	ds_read_b128 v[176:179], v195 offset:20992
	ds_read_b128 v[84:87], v195 offset:37376
	ds_read_b64 v[4:5], v196 offset:9216
	ds_read_b32 v6, v36 offset:9216
	s_waitcnt lgkmcnt(6)
	v_pk_mul_f32 v[46:47], v[24:25], v[144:145] op_sel_hi:[0,1]
	v_pk_mul_f32 v[34:35], v[20:21], v[144:145] op_sel_hi:[0,1]
	v_pk_fma_f32 v[46:47], v[24:25], v[146:147], v[46:47] op_sel:[1,0,0] op_sel_hi:[1,1,1]
	v_pk_fma_f32 v[34:35], v[20:21], v[146:147], v[34:35] op_sel:[1,0,0] op_sel_hi:[1,1,1]
	v_pk_fma_f32 v[46:47], v[26:27], v[156:157], v[46:47] op_sel_hi:[0,1,1]
	v_pk_fma_f32 v[34:35], v[22:23], v[156:157], v[34:35] op_sel_hi:[0,1,1]
	v_pk_fma_f32 v[46:47], v[26:27], v[158:159], v[46:47] op_sel:[1,0,0] op_sel_hi:[1,1,1]
	v_pk_fma_f32 v[34:35], v[22:23], v[158:159], v[34:35] op_sel:[1,0,0] op_sel_hi:[1,1,1]
	v_pk_fma_f32 v[20:21], v[180:181], v[8:9], v[20:21] op_sel_hi:[1,0,1]
	v_add_f32_dpp v28, v46, v34 row_half_mirror row_mask:0xf bank_mask:0xf
	v_add_f32_dpp v149, v47, v35 row_half_mirror row_mask:0xf bank_mask:0xf
	v_pk_fma_f32 v[22:23], v[182:183], v[8:9], v[22:23] op_sel_hi:[1,0,1]
	v_add_f32_dpp v28, v28, v28 row_ror:8 row_mask:0xf bank_mask:0xf
	v_pk_fma_f32 v[24:25], v[180:181], v[10:11], v[24:25] op_sel_hi:[1,0,1]
	v_pk_fma_f32 v[26:27], v[182:183], v[10:11], v[26:27] op_sel_hi:[1,0,1]
	v_add_f32_dpp v28, v28, v28 quad_perm:[1,0,3,2] row_mask:0xf bank_mask:0xf
	v_fmac_f32_e32 v149, 0x3e000000, v9
	v_add_f32_dpp v163, v175, v175 row_ror:8 row_mask:0xf bank_mask:0xc
	v_add_f32_dpp v28, v28, v28 quad_perm:[2,3,0,1] row_mask:0xf bank_mask:0xf
	v_pk_fma_f32 v[20:21], v[88:89], v[28:29], v[20:21] op_sel_hi:[1,0,1] neg_lo:[0,1,0] neg_hi:[0,1,0]
	v_pk_fma_f32 v[22:23], v[90:91], v[28:29], v[22:23] op_sel_hi:[1,0,1] neg_lo:[0,1,0] neg_hi:[0,1,0]
	v_mov_b32_dpp v30, v28 row_half_mirror row_mask:0xf bank_mask:0xf
	v_pk_fma_f32 v[24:25], v[88:89], v[30:31], v[24:25] op_sel_hi:[1,0,1] neg_lo:[0,1,0] neg_hi:[0,1,0]
	v_pk_fma_f32 v[26:27], v[90:91], v[30:31], v[26:27] op_sel_hi:[1,0,1] neg_lo:[0,1,0] neg_hi:[0,1,0]
	v_add_f32_dpp v162, v162, v162 quad_perm:[1,0,3,2] row_mask:0xf bank_mask:0xf
	v_add_f32_dpp v163, v163, v163 quad_perm:[1,0,3,2] row_mask:0xf bank_mask:0xf
	ds_read_b128 v[144:147], v195 offset:4864
	ds_read_b128 v[156:159], v195 offset:13056
	ds_read_b128 v[168:171], v195 offset:29440
	ds_read_b128 v[180:183], v195 offset:21248
	ds_read_b128 v[88:91], v195 offset:37632
	ds_read_b64 v[8:9], v196 offset:9728
	ds_read_b32 v10, v36 offset:9728
	s_waitcnt lgkmcnt(7)
	v_pk_mul_f32 v[46:47], v[24:25], v[140:141] op_sel_hi:[0,1]
	v_pk_mul_f32 v[34:35], v[20:21], v[140:141] op_sel_hi:[0,1]
	v_pk_fma_f32 v[46:47], v[24:25], v[142:143], v[46:47] op_sel:[1,0,0] op_sel_hi:[1,1,1]
	v_pk_fma_f32 v[34:35], v[20:21], v[142:143], v[34:35] op_sel:[1,0,0] op_sel_hi:[1,1,1]
	v_pk_fma_f32 v[46:47], v[26:27], v[152:153], v[46:47] op_sel_hi:[0,1,1]
	v_pk_fma_f32 v[34:35], v[22:23], v[152:153], v[34:35] op_sel_hi:[0,1,1]
	v_pk_fma_f32 v[46:47], v[26:27], v[154:155], v[46:47] op_sel:[1,0,0] op_sel_hi:[1,1,1]
	v_pk_fma_f32 v[34:35], v[22:23], v[154:155], v[34:35] op_sel:[1,0,0] op_sel_hi:[1,1,1]
	v_pk_fma_f32 v[20:21], v[176:177], v[4:5], v[20:21] op_sel_hi:[1,0,1]
	v_add_f32_dpp v28, v46, v34 row_half_mirror row_mask:0xf bank_mask:0xf
	v_add_f32_dpp v150, v47, v35 row_half_mirror row_mask:0xf bank_mask:0xf
	v_pk_fma_f32 v[22:23], v[178:179], v[4:5], v[22:23] op_sel_hi:[1,0,1]
	v_add_f32_dpp v28, v28, v28 row_ror:8 row_mask:0xf bank_mask:0xf
	v_pk_fma_f32 v[24:25], v[176:177], v[6:7], v[24:25] op_sel_hi:[1,0,1]
	v_pk_fma_f32 v[26:27], v[178:179], v[6:7], v[26:27] op_sel_hi:[1,0,1]
	v_add_f32_dpp v28, v28, v28 quad_perm:[1,0,3,2] row_mask:0xf bank_mask:0xf
	v_fmac_f32_e32 v150, 0x3e000000, v5
	v_add_f32_dpp v162, v162, v162 quad_perm:[2,3,0,1] row_mask:0xf bank_mask:0xf
	v_add_f32_dpp v28, v28, v28 quad_perm:[2,3,0,1] row_mask:0xf bank_mask:0xf
	v_pk_fma_f32 v[20:21], v[84:85], v[28:29], v[20:21] op_sel_hi:[1,0,1] neg_lo:[0,1,0] neg_hi:[0,1,0]
	v_pk_fma_f32 v[22:23], v[86:87], v[28:29], v[22:23] op_sel_hi:[1,0,1] neg_lo:[0,1,0] neg_hi:[0,1,0]
	v_mov_b32_dpp v30, v28 row_half_mirror row_mask:0xf bank_mask:0xf
	v_pk_fma_f32 v[24:25], v[84:85], v[30:31], v[24:25] op_sel_hi:[1,0,1] neg_lo:[0,1,0] neg_hi:[0,1,0]
	v_pk_fma_f32 v[26:27], v[86:87], v[30:31], v[26:27] op_sel_hi:[1,0,1] neg_lo:[0,1,0] neg_hi:[0,1,0]
	v_add_f32_dpp v163, v163, v163 quad_perm:[2,3,0,1] row_mask:0xf bank_mask:0xf
	ds_write_b32 v102, v162 offset:1536
	ds_read_b128 v[140:143], v195 offset:5120
	ds_read_b128 v[152:155], v195 offset:13312
	ds_read_b128 v[176:179], v195 offset:21504
	ds_read_b128 v[84:87], v195 offset:37888
	ds_read_b64 v[4:5], v196 offset:10240
	ds_read_b32 v6, v36 offset:10240
	s_waitcnt lgkmcnt(7)
	v_pk_mul_f32 v[46:47], v[24:25], v[144:145] op_sel_hi:[0,1]
	v_pk_mul_f32 v[34:35], v[20:21], v[144:145] op_sel_hi:[0,1]
	v_pk_fma_f32 v[46:47], v[24:25], v[146:147], v[46:47] op_sel:[1,0,0] op_sel_hi:[1,1,1]
	v_pk_fma_f32 v[34:35], v[20:21], v[146:147], v[34:35] op_sel:[1,0,0] op_sel_hi:[1,1,1]
	v_pk_fma_f32 v[46:47], v[26:27], v[156:157], v[46:47] op_sel_hi:[0,1,1]
	v_pk_fma_f32 v[34:35], v[22:23], v[156:157], v[34:35] op_sel_hi:[0,1,1]
	v_pk_fma_f32 v[46:47], v[26:27], v[158:159], v[46:47] op_sel:[1,0,0] op_sel_hi:[1,1,1]
	v_pk_fma_f32 v[34:35], v[22:23], v[158:159], v[34:35] op_sel:[1,0,0] op_sel_hi:[1,1,1]
	v_pk_mul_f32 v[20:21], v[20:21], v[168:169]
	v_add_f32_dpp v28, v46, v34 row_half_mirror row_mask:0xf bank_mask:0xf
	v_add_f32_dpp v151, v47, v35 row_half_mirror row_mask:0xf bank_mask:0xf
	v_pk_mul_f32 v[22:23], v[22:23], v[170:171]
	v_add_f32_dpp v28, v28, v28 row_ror:8 row_mask:0xf bank_mask:0xf
	v_pk_mul_f32 v[24:25], v[24:25], v[168:169]
	v_pk_mul_f32 v[26:27], v[26:27], v[170:171]
	v_add_f32_dpp v28, v28, v28 quad_perm:[1,0,3,2] row_mask:0xf bank_mask:0xf
	v_pk_fma_f32 v[20:21], v[180:181], v[8:9], v[20:21] op_sel_hi:[1,0,1]
	v_pk_fma_f32 v[22:23], v[182:183], v[8:9], v[22:23] op_sel_hi:[1,0,1]
	v_add_f32_dpp v28, v28, v28 quad_perm:[2,3,0,1] row_mask:0xf bank_mask:0xf
	v_pk_fma_f32 v[24:25], v[180:181], v[10:11], v[24:25] op_sel_hi:[1,0,1]
	v_pk_fma_f32 v[26:27], v[182:183], v[10:11], v[26:27] op_sel_hi:[1,0,1]
	v_mov_b32_dpp v30, v28 row_half_mirror row_mask:0xf bank_mask:0xf
	v_fmac_f32_e32 v151, 0x3e000000, v9
	v_pk_fma_f32 v[20:21], v[88:89], v[28:29], v[20:21] op_sel_hi:[1,0,1] neg_lo:[0,1,0] neg_hi:[0,1,0]
	v_pk_fma_f32 v[22:23], v[90:91], v[28:29], v[22:23] op_sel_hi:[1,0,1] neg_lo:[0,1,0] neg_hi:[0,1,0]
	v_pk_fma_f32 v[24:25], v[88:89], v[30:31], v[24:25] op_sel_hi:[1,0,1] neg_lo:[0,1,0] neg_hi:[0,1,0]
	v_pk_fma_f32 v[26:27], v[90:91], v[30:31], v[26:27] op_sel_hi:[1,0,1] neg_lo:[0,1,0] neg_hi:[0,1,0]
	ds_write_b32 v102, v163 offset:1792
	ds_read_b128 v[144:147], v195 offset:5376
	ds_read_b128 v[156:159], v195 offset:13568
	ds_read_b128 v[180:183], v195 offset:21760
	ds_read_b128 v[88:91], v195 offset:38144
	ds_read_b64 v[8:9], v196 offset:10752
	ds_read_b32 v10, v36 offset:10752
	s_waitcnt lgkmcnt(7)
	v_pk_mul_f32 v[46:47], v[24:25], v[140:141] op_sel_hi:[0,1]
	v_pk_mul_f32 v[34:35], v[20:21], v[140:141] op_sel_hi:[0,1]
	v_pk_fma_f32 v[46:47], v[24:25], v[142:143], v[46:47] op_sel:[1,0,0] op_sel_hi:[1,1,1]
	v_pk_fma_f32 v[34:35], v[20:21], v[142:143], v[34:35] op_sel:[1,0,0] op_sel_hi:[1,1,1]
	v_pk_fma_f32 v[46:47], v[26:27], v[152:153], v[46:47] op_sel_hi:[0,1,1]
	v_pk_fma_f32 v[34:35], v[22:23], v[152:153], v[34:35] op_sel_hi:[0,1,1]
	v_pk_fma_f32 v[46:47], v[26:27], v[154:155], v[46:47] op_sel:[1,0,0] op_sel_hi:[1,1,1]
	v_pk_fma_f32 v[34:35], v[22:23], v[154:155], v[34:35] op_sel:[1,0,0] op_sel_hi:[1,1,1]
	v_pk_fma_f32 v[20:21], v[176:177], v[4:5], v[20:21] op_sel_hi:[1,0,1]
	v_add_f32_dpp v28, v46, v34 row_half_mirror row_mask:0xf bank_mask:0xf
	v_add_f32_dpp v172, v47, v35 row_half_mirror row_mask:0xf bank_mask:0xf
	v_pk_fma_f32 v[22:23], v[178:179], v[4:5], v[22:23] op_sel_hi:[1,0,1]
	v_add_f32_dpp v28, v28, v28 row_ror:8 row_mask:0xf bank_mask:0xf
	v_pk_fma_f32 v[24:25], v[176:177], v[6:7], v[24:25] op_sel_hi:[1,0,1]
	v_pk_fma_f32 v[26:27], v[178:179], v[6:7], v[26:27] op_sel_hi:[1,0,1]
	v_add_f32_dpp v28, v28, v28 quad_perm:[1,0,3,2] row_mask:0xf bank_mask:0xf
	v_fmac_f32_e32 v172, 0x3e000000, v5
	v_add_f32_dpp v160, v148, v148 row_ror:8 row_mask:0xf bank_mask:0x3
	v_add_f32_dpp v28, v28, v28 quad_perm:[2,3,0,1] row_mask:0xf bank_mask:0xf
	v_pk_fma_f32 v[20:21], v[84:85], v[28:29], v[20:21] op_sel_hi:[1,0,1] neg_lo:[0,1,0] neg_hi:[0,1,0]
	v_pk_fma_f32 v[22:23], v[86:87], v[28:29], v[22:23] op_sel_hi:[1,0,1] neg_lo:[0,1,0] neg_hi:[0,1,0]
	v_mov_b32_dpp v30, v28 row_half_mirror row_mask:0xf bank_mask:0xf
	v_pk_fma_f32 v[24:25], v[84:85], v[30:31], v[24:25] op_sel_hi:[1,0,1] neg_lo:[0,1,0] neg_hi:[0,1,0]
	v_pk_fma_f32 v[26:27], v[86:87], v[30:31], v[26:27] op_sel_hi:[1,0,1] neg_lo:[0,1,0] neg_hi:[0,1,0]
	v_add_f32_dpp v160, v149, v149 row_ror:8 row_mask:0xf bank_mask:0xc
	v_add_f32_dpp v161, v150, v150 row_ror:8 row_mask:0xf bank_mask:0x3
	ds_read_b128 v[140:143], v195 offset:5632
	ds_read_b128 v[152:155], v195 offset:13824
	ds_read_b128 v[176:179], v195 offset:22016
	ds_read_b128 v[84:87], v195 offset:38400
	ds_read_b64 v[4:5], v196 offset:11264
	ds_read_b32 v6, v36 offset:11264
	s_waitcnt lgkmcnt(6)
	v_pk_mul_f32 v[46:47], v[24:25], v[144:145] op_sel_hi:[0,1]
	v_pk_mul_f32 v[34:35], v[20:21], v[144:145] op_sel_hi:[0,1]
	v_pk_fma_f32 v[46:47], v[24:25], v[146:147], v[46:47] op_sel:[1,0,0] op_sel_hi:[1,1,1]
	v_pk_fma_f32 v[34:35], v[20:21], v[146:147], v[34:35] op_sel:[1,0,0] op_sel_hi:[1,1,1]
	v_pk_fma_f32 v[46:47], v[26:27], v[156:157], v[46:47] op_sel_hi:[0,1,1]
	v_pk_fma_f32 v[34:35], v[22:23], v[156:157], v[34:35] op_sel_hi:[0,1,1]
	v_pk_fma_f32 v[46:47], v[26:27], v[158:159], v[46:47] op_sel:[1,0,0] op_sel_hi:[1,1,1]
	v_pk_fma_f32 v[34:35], v[22:23], v[158:159], v[34:35] op_sel:[1,0,0] op_sel_hi:[1,1,1]
	v_pk_fma_f32 v[20:21], v[180:181], v[8:9], v[20:21] op_sel_hi:[1,0,1]
	v_add_f32_dpp v28, v46, v34 row_half_mirror row_mask:0xf bank_mask:0xf
	v_add_f32_dpp v173, v47, v35 row_half_mirror row_mask:0xf bank_mask:0xf
	v_pk_fma_f32 v[22:23], v[182:183], v[8:9], v[22:23] op_sel_hi:[1,0,1]
	v_add_f32_dpp v28, v28, v28 row_ror:8 row_mask:0xf bank_mask:0xf
	v_pk_fma_f32 v[24:25], v[180:181], v[10:11], v[24:25] op_sel_hi:[1,0,1]
	v_pk_fma_f32 v[26:27], v[182:183], v[10:11], v[26:27] op_sel_hi:[1,0,1]
	v_add_f32_dpp v28, v28, v28 quad_perm:[1,0,3,2] row_mask:0xf bank_mask:0xf
	v_fmac_f32_e32 v173, 0x3e000000, v9
	v_add_f32_dpp v161, v151, v151 row_ror:8 row_mask:0xf bank_mask:0xc
	v_add_f32_dpp v28, v28, v28 quad_perm:[2,3,0,1] row_mask:0xf bank_mask:0xf
	v_pk_fma_f32 v[20:21], v[88:89], v[28:29], v[20:21] op_sel_hi:[1,0,1] neg_lo:[0,1,0] neg_hi:[0,1,0]
	v_pk_fma_f32 v[22:23], v[90:91], v[28:29], v[22:23] op_sel_hi:[1,0,1] neg_lo:[0,1,0] neg_hi:[0,1,0]
	v_mov_b32_dpp v30, v28 row_half_mirror row_mask:0xf bank_mask:0xf
	v_pk_fma_f32 v[24:25], v[88:89], v[30:31], v[24:25] op_sel_hi:[1,0,1] neg_lo:[0,1,0] neg_hi:[0,1,0]
	v_pk_fma_f32 v[26:27], v[90:91], v[30:31], v[26:27] op_sel_hi:[1,0,1] neg_lo:[0,1,0] neg_hi:[0,1,0]
	v_add_f32_dpp v160, v160, v160 quad_perm:[1,0,3,2] row_mask:0xf bank_mask:0xf
	v_add_f32_dpp v161, v161, v161 quad_perm:[1,0,3,2] row_mask:0xf bank_mask:0xf
	ds_read_b128 v[144:147], v195 offset:5888
	ds_read_b128 v[156:159], v195 offset:14080
	ds_read_b128 v[168:171], v195 offset:30464
	ds_read_b128 v[180:183], v195 offset:22272
	ds_read_b128 v[88:91], v195 offset:38656
	ds_read_b64 v[8:9], v196 offset:11776
	ds_read_b32 v10, v36 offset:11776
	s_waitcnt lgkmcnt(7)
	v_pk_mul_f32 v[46:47], v[24:25], v[140:141] op_sel_hi:[0,1]
	v_pk_mul_f32 v[34:35], v[20:21], v[140:141] op_sel_hi:[0,1]
	v_pk_fma_f32 v[46:47], v[24:25], v[142:143], v[46:47] op_sel:[1,0,0] op_sel_hi:[1,1,1]
	v_pk_fma_f32 v[34:35], v[20:21], v[142:143], v[34:35] op_sel:[1,0,0] op_sel_hi:[1,1,1]
	v_pk_fma_f32 v[46:47], v[26:27], v[152:153], v[46:47] op_sel_hi:[0,1,1]
	v_pk_fma_f32 v[34:35], v[22:23], v[152:153], v[34:35] op_sel_hi:[0,1,1]
	v_pk_fma_f32 v[46:47], v[26:27], v[154:155], v[46:47] op_sel:[1,0,0] op_sel_hi:[1,1,1]
	v_pk_fma_f32 v[34:35], v[22:23], v[154:155], v[34:35] op_sel:[1,0,0] op_sel_hi:[1,1,1]
	v_pk_fma_f32 v[20:21], v[176:177], v[4:5], v[20:21] op_sel_hi:[1,0,1]
	v_add_f32_dpp v28, v46, v34 row_half_mirror row_mask:0xf bank_mask:0xf
	v_add_f32_dpp v174, v47, v35 row_half_mirror row_mask:0xf bank_mask:0xf
	v_pk_fma_f32 v[22:23], v[178:179], v[4:5], v[22:23] op_sel_hi:[1,0,1]
	v_add_f32_dpp v28, v28, v28 row_ror:8 row_mask:0xf bank_mask:0xf
	v_pk_fma_f32 v[24:25], v[176:177], v[6:7], v[24:25] op_sel_hi:[1,0,1]
	v_pk_fma_f32 v[26:27], v[178:179], v[6:7], v[26:27] op_sel_hi:[1,0,1]
	v_add_f32_dpp v28, v28, v28 quad_perm:[1,0,3,2] row_mask:0xf bank_mask:0xf
	v_fmac_f32_e32 v174, 0x3e000000, v5
	v_add_f32_dpp v160, v160, v160 quad_perm:[2,3,0,1] row_mask:0xf bank_mask:0xf
	v_add_f32_dpp v28, v28, v28 quad_perm:[2,3,0,1] row_mask:0xf bank_mask:0xf
	v_pk_fma_f32 v[20:21], v[84:85], v[28:29], v[20:21] op_sel_hi:[1,0,1] neg_lo:[0,1,0] neg_hi:[0,1,0]
	v_pk_fma_f32 v[22:23], v[86:87], v[28:29], v[22:23] op_sel_hi:[1,0,1] neg_lo:[0,1,0] neg_hi:[0,1,0]
	v_mov_b32_dpp v30, v28 row_half_mirror row_mask:0xf bank_mask:0xf
	v_pk_fma_f32 v[24:25], v[84:85], v[30:31], v[24:25] op_sel_hi:[1,0,1] neg_lo:[0,1,0] neg_hi:[0,1,0]
	v_pk_fma_f32 v[26:27], v[86:87], v[30:31], v[26:27] op_sel_hi:[1,0,1] neg_lo:[0,1,0] neg_hi:[0,1,0]
	v_add_f32_dpp v161, v161, v161 quad_perm:[2,3,0,1] row_mask:0xf bank_mask:0xf
	ds_write_b32 v102, v160 offset:2048
	ds_read_b128 v[140:143], v195 offset:6144
	ds_read_b128 v[152:155], v195 offset:14336
	ds_read_b128 v[176:179], v195 offset:22528
	ds_read_b128 v[84:87], v195 offset:38912
	ds_read_b64 v[4:5], v196 offset:12288
	ds_read_b32 v6, v36 offset:12288
	s_waitcnt lgkmcnt(7)
	v_pk_mul_f32 v[46:47], v[24:25], v[144:145] op_sel_hi:[0,1]
	v_pk_mul_f32 v[34:35], v[20:21], v[144:145] op_sel_hi:[0,1]
	v_pk_fma_f32 v[46:47], v[24:25], v[146:147], v[46:47] op_sel:[1,0,0] op_sel_hi:[1,1,1]
	v_pk_fma_f32 v[34:35], v[20:21], v[146:147], v[34:35] op_sel:[1,0,0] op_sel_hi:[1,1,1]
	v_pk_fma_f32 v[46:47], v[26:27], v[156:157], v[46:47] op_sel_hi:[0,1,1]
	v_pk_fma_f32 v[34:35], v[22:23], v[156:157], v[34:35] op_sel_hi:[0,1,1]
	v_pk_fma_f32 v[46:47], v[26:27], v[158:159], v[46:47] op_sel:[1,0,0] op_sel_hi:[1,1,1]
	v_pk_fma_f32 v[34:35], v[22:23], v[158:159], v[34:35] op_sel:[1,0,0] op_sel_hi:[1,1,1]
	v_pk_mul_f32 v[20:21], v[20:21], v[168:169]
	v_add_f32_dpp v28, v46, v34 row_half_mirror row_mask:0xf bank_mask:0xf
	v_add_f32_dpp v175, v47, v35 row_half_mirror row_mask:0xf bank_mask:0xf
	v_pk_mul_f32 v[22:23], v[22:23], v[170:171]
	v_add_f32_dpp v28, v28, v28 row_ror:8 row_mask:0xf bank_mask:0xf
	v_pk_mul_f32 v[24:25], v[24:25], v[168:169]
	v_pk_mul_f32 v[26:27], v[26:27], v[170:171]
	v_add_f32_dpp v28, v28, v28 quad_perm:[1,0,3,2] row_mask:0xf bank_mask:0xf
	v_pk_fma_f32 v[20:21], v[180:181], v[8:9], v[20:21] op_sel_hi:[1,0,1]
	v_pk_fma_f32 v[22:23], v[182:183], v[8:9], v[22:23] op_sel_hi:[1,0,1]
	v_add_f32_dpp v28, v28, v28 quad_perm:[2,3,0,1] row_mask:0xf bank_mask:0xf
	v_pk_fma_f32 v[24:25], v[180:181], v[10:11], v[24:25] op_sel_hi:[1,0,1]
	v_pk_fma_f32 v[26:27], v[182:183], v[10:11], v[26:27] op_sel_hi:[1,0,1]
	v_mov_b32_dpp v30, v28 row_half_mirror row_mask:0xf bank_mask:0xf
	v_fmac_f32_e32 v175, 0x3e000000, v9
	v_pk_fma_f32 v[20:21], v[88:89], v[28:29], v[20:21] op_sel_hi:[1,0,1] neg_lo:[0,1,0] neg_hi:[0,1,0]
	v_pk_fma_f32 v[22:23], v[90:91], v[28:29], v[22:23] op_sel_hi:[1,0,1] neg_lo:[0,1,0] neg_hi:[0,1,0]
	v_pk_fma_f32 v[24:25], v[88:89], v[30:31], v[24:25] op_sel_hi:[1,0,1] neg_lo:[0,1,0] neg_hi:[0,1,0]
	v_pk_fma_f32 v[26:27], v[90:91], v[30:31], v[26:27] op_sel_hi:[1,0,1] neg_lo:[0,1,0] neg_hi:[0,1,0]
	ds_write_b32 v102, v161 offset:2304
	ds_read_b128 v[144:147], v195 offset:6400
	ds_read_b128 v[156:159], v195 offset:14592
	ds_read_b128 v[180:183], v195 offset:22784
	ds_read_b128 v[88:91], v195 offset:39168
	ds_read_b64 v[8:9], v196 offset:12800
	ds_read_b32 v10, v36 offset:12800
	s_waitcnt lgkmcnt(7)
	v_pk_mul_f32 v[46:47], v[24:25], v[140:141] op_sel_hi:[0,1]
	v_pk_mul_f32 v[34:35], v[20:21], v[140:141] op_sel_hi:[0,1]
	v_pk_fma_f32 v[46:47], v[24:25], v[142:143], v[46:47] op_sel:[1,0,0] op_sel_hi:[1,1,1]
	v_pk_fma_f32 v[34:35], v[20:21], v[142:143], v[34:35] op_sel:[1,0,0] op_sel_hi:[1,1,1]
	v_pk_fma_f32 v[46:47], v[26:27], v[152:153], v[46:47] op_sel_hi:[0,1,1]
	v_pk_fma_f32 v[34:35], v[22:23], v[152:153], v[34:35] op_sel_hi:[0,1,1]
	v_pk_fma_f32 v[46:47], v[26:27], v[154:155], v[46:47] op_sel:[1,0,0] op_sel_hi:[1,1,1]
	v_pk_fma_f32 v[34:35], v[22:23], v[154:155], v[34:35] op_sel:[1,0,0] op_sel_hi:[1,1,1]
	v_pk_fma_f32 v[20:21], v[176:177], v[4:5], v[20:21] op_sel_hi:[1,0,1]
	v_add_f32_dpp v28, v46, v34 row_half_mirror row_mask:0xf bank_mask:0xf
	v_add_f32_dpp v148, v47, v35 row_half_mirror row_mask:0xf bank_mask:0xf
	v_pk_fma_f32 v[22:23], v[178:179], v[4:5], v[22:23] op_sel_hi:[1,0,1]
	v_add_f32_dpp v28, v28, v28 row_ror:8 row_mask:0xf bank_mask:0xf
	v_pk_fma_f32 v[24:25], v[176:177], v[6:7], v[24:25] op_sel_hi:[1,0,1]
	v_pk_fma_f32 v[26:27], v[178:179], v[6:7], v[26:27] op_sel_hi:[1,0,1]
	v_add_f32_dpp v28, v28, v28 quad_perm:[1,0,3,2] row_mask:0xf bank_mask:0xf
	v_fmac_f32_e32 v148, 0x3e000000, v5
	v_add_f32_dpp v162, v172, v172 row_ror:8 row_mask:0xf bank_mask:0x3
	v_add_f32_dpp v28, v28, v28 quad_perm:[2,3,0,1] row_mask:0xf bank_mask:0xf
	v_pk_fma_f32 v[20:21], v[84:85], v[28:29], v[20:21] op_sel_hi:[1,0,1] neg_lo:[0,1,0] neg_hi:[0,1,0]
	v_pk_fma_f32 v[22:23], v[86:87], v[28:29], v[22:23] op_sel_hi:[1,0,1] neg_lo:[0,1,0] neg_hi:[0,1,0]
	v_mov_b32_dpp v30, v28 row_half_mirror row_mask:0xf bank_mask:0xf
	v_pk_fma_f32 v[24:25], v[84:85], v[30:31], v[24:25] op_sel_hi:[1,0,1] neg_lo:[0,1,0] neg_hi:[0,1,0]
	v_pk_fma_f32 v[26:27], v[86:87], v[30:31], v[26:27] op_sel_hi:[1,0,1] neg_lo:[0,1,0] neg_hi:[0,1,0]
	v_add_f32_dpp v162, v173, v173 row_ror:8 row_mask:0xf bank_mask:0xc
	v_add_f32_dpp v163, v174, v174 row_ror:8 row_mask:0xf bank_mask:0x3
	ds_read_b128 v[140:143], v195 offset:6656
	ds_read_b128 v[152:155], v195 offset:14848
	ds_read_b128 v[176:179], v195 offset:23040
	ds_read_b128 v[84:87], v195 offset:39424
	ds_read_b64 v[4:5], v196 offset:13312
	ds_read_b32 v6, v36 offset:13312
	s_waitcnt lgkmcnt(6)
	v_pk_mul_f32 v[46:47], v[24:25], v[144:145] op_sel_hi:[0,1]
	v_pk_mul_f32 v[34:35], v[20:21], v[144:145] op_sel_hi:[0,1]
	v_pk_fma_f32 v[46:47], v[24:25], v[146:147], v[46:47] op_sel:[1,0,0] op_sel_hi:[1,1,1]
	v_pk_fma_f32 v[34:35], v[20:21], v[146:147], v[34:35] op_sel:[1,0,0] op_sel_hi:[1,1,1]
	v_pk_fma_f32 v[46:47], v[26:27], v[156:157], v[46:47] op_sel_hi:[0,1,1]
	v_pk_fma_f32 v[34:35], v[22:23], v[156:157], v[34:35] op_sel_hi:[0,1,1]
	v_pk_fma_f32 v[46:47], v[26:27], v[158:159], v[46:47] op_sel:[1,0,0] op_sel_hi:[1,1,1]
	v_pk_fma_f32 v[34:35], v[22:23], v[158:159], v[34:35] op_sel:[1,0,0] op_sel_hi:[1,1,1]
	v_pk_fma_f32 v[20:21], v[180:181], v[8:9], v[20:21] op_sel_hi:[1,0,1]
	v_add_f32_dpp v28, v46, v34 row_half_mirror row_mask:0xf bank_mask:0xf
	v_add_f32_dpp v149, v47, v35 row_half_mirror row_mask:0xf bank_mask:0xf
	v_pk_fma_f32 v[22:23], v[182:183], v[8:9], v[22:23] op_sel_hi:[1,0,1]
	v_add_f32_dpp v28, v28, v28 row_ror:8 row_mask:0xf bank_mask:0xf
	v_pk_fma_f32 v[24:25], v[180:181], v[10:11], v[24:25] op_sel_hi:[1,0,1]
	v_pk_fma_f32 v[26:27], v[182:183], v[10:11], v[26:27] op_sel_hi:[1,0,1]
	v_add_f32_dpp v28, v28, v28 quad_perm:[1,0,3,2] row_mask:0xf bank_mask:0xf
	v_fmac_f32_e32 v149, 0x3e000000, v9
	v_add_f32_dpp v163, v175, v175 row_ror:8 row_mask:0xf bank_mask:0xc
	v_add_f32_dpp v28, v28, v28 quad_perm:[2,3,0,1] row_mask:0xf bank_mask:0xf
	v_pk_fma_f32 v[20:21], v[88:89], v[28:29], v[20:21] op_sel_hi:[1,0,1] neg_lo:[0,1,0] neg_hi:[0,1,0]
	v_pk_fma_f32 v[22:23], v[90:91], v[28:29], v[22:23] op_sel_hi:[1,0,1] neg_lo:[0,1,0] neg_hi:[0,1,0]
	v_mov_b32_dpp v30, v28 row_half_mirror row_mask:0xf bank_mask:0xf
	v_pk_fma_f32 v[24:25], v[88:89], v[30:31], v[24:25] op_sel_hi:[1,0,1] neg_lo:[0,1,0] neg_hi:[0,1,0]
	v_pk_fma_f32 v[26:27], v[90:91], v[30:31], v[26:27] op_sel_hi:[1,0,1] neg_lo:[0,1,0] neg_hi:[0,1,0]
	v_add_f32_dpp v162, v162, v162 quad_perm:[1,0,3,2] row_mask:0xf bank_mask:0xf
	v_add_f32_dpp v163, v163, v163 quad_perm:[1,0,3,2] row_mask:0xf bank_mask:0xf
	ds_read_b128 v[144:147], v195 offset:6912
	ds_read_b128 v[156:159], v195 offset:15104
	ds_read_b128 v[168:171], v195 offset:31488
	ds_read_b128 v[180:183], v195 offset:23296
	ds_read_b128 v[88:91], v195 offset:39680
	ds_read_b64 v[8:9], v196 offset:13824
	ds_read_b32 v10, v36 offset:13824
	s_waitcnt lgkmcnt(7)
	v_pk_mul_f32 v[46:47], v[24:25], v[140:141] op_sel_hi:[0,1]
	v_pk_mul_f32 v[34:35], v[20:21], v[140:141] op_sel_hi:[0,1]
	v_pk_fma_f32 v[46:47], v[24:25], v[142:143], v[46:47] op_sel:[1,0,0] op_sel_hi:[1,1,1]
	v_pk_fma_f32 v[34:35], v[20:21], v[142:143], v[34:35] op_sel:[1,0,0] op_sel_hi:[1,1,1]
	v_pk_fma_f32 v[46:47], v[26:27], v[152:153], v[46:47] op_sel_hi:[0,1,1]
	v_pk_fma_f32 v[34:35], v[22:23], v[152:153], v[34:35] op_sel_hi:[0,1,1]
	v_pk_fma_f32 v[46:47], v[26:27], v[154:155], v[46:47] op_sel:[1,0,0] op_sel_hi:[1,1,1]
	v_pk_fma_f32 v[34:35], v[22:23], v[154:155], v[34:35] op_sel:[1,0,0] op_sel_hi:[1,1,1]
	v_pk_fma_f32 v[20:21], v[176:177], v[4:5], v[20:21] op_sel_hi:[1,0,1]
	v_add_f32_dpp v28, v46, v34 row_half_mirror row_mask:0xf bank_mask:0xf
	v_add_f32_dpp v150, v47, v35 row_half_mirror row_mask:0xf bank_mask:0xf
	v_pk_fma_f32 v[22:23], v[178:179], v[4:5], v[22:23] op_sel_hi:[1,0,1]
	v_add_f32_dpp v28, v28, v28 row_ror:8 row_mask:0xf bank_mask:0xf
	v_pk_fma_f32 v[24:25], v[176:177], v[6:7], v[24:25] op_sel_hi:[1,0,1]
	v_pk_fma_f32 v[26:27], v[178:179], v[6:7], v[26:27] op_sel_hi:[1,0,1]
	v_add_f32_dpp v28, v28, v28 quad_perm:[1,0,3,2] row_mask:0xf bank_mask:0xf
	v_fmac_f32_e32 v150, 0x3e000000, v5
	v_add_f32_dpp v162, v162, v162 quad_perm:[2,3,0,1] row_mask:0xf bank_mask:0xf
	v_add_f32_dpp v28, v28, v28 quad_perm:[2,3,0,1] row_mask:0xf bank_mask:0xf
	v_pk_fma_f32 v[20:21], v[84:85], v[28:29], v[20:21] op_sel_hi:[1,0,1] neg_lo:[0,1,0] neg_hi:[0,1,0]
	v_pk_fma_f32 v[22:23], v[86:87], v[28:29], v[22:23] op_sel_hi:[1,0,1] neg_lo:[0,1,0] neg_hi:[0,1,0]
	v_mov_b32_dpp v30, v28 row_half_mirror row_mask:0xf bank_mask:0xf
	v_pk_fma_f32 v[24:25], v[84:85], v[30:31], v[24:25] op_sel_hi:[1,0,1] neg_lo:[0,1,0] neg_hi:[0,1,0]
	v_pk_fma_f32 v[26:27], v[86:87], v[30:31], v[26:27] op_sel_hi:[1,0,1] neg_lo:[0,1,0] neg_hi:[0,1,0]
	v_add_f32_dpp v163, v163, v163 quad_perm:[2,3,0,1] row_mask:0xf bank_mask:0xf
	ds_write_b32 v102, v162 offset:2560
	ds_read_b128 v[140:143], v195 offset:7168
	ds_read_b128 v[152:155], v195 offset:15360
	ds_read_b128 v[176:179], v195 offset:23552
	ds_read_b128 v[84:87], v195 offset:39936
	ds_read_b64 v[4:5], v196 offset:14336
	ds_read_b32 v6, v36 offset:14336
	s_waitcnt lgkmcnt(7)
	v_pk_mul_f32 v[46:47], v[24:25], v[144:145] op_sel_hi:[0,1]
	v_pk_mul_f32 v[34:35], v[20:21], v[144:145] op_sel_hi:[0,1]
	v_pk_fma_f32 v[46:47], v[24:25], v[146:147], v[46:47] op_sel:[1,0,0] op_sel_hi:[1,1,1]
	v_pk_fma_f32 v[34:35], v[20:21], v[146:147], v[34:35] op_sel:[1,0,0] op_sel_hi:[1,1,1]
	v_pk_fma_f32 v[46:47], v[26:27], v[156:157], v[46:47] op_sel_hi:[0,1,1]
	v_pk_fma_f32 v[34:35], v[22:23], v[156:157], v[34:35] op_sel_hi:[0,1,1]
	v_pk_fma_f32 v[46:47], v[26:27], v[158:159], v[46:47] op_sel:[1,0,0] op_sel_hi:[1,1,1]
	v_pk_fma_f32 v[34:35], v[22:23], v[158:159], v[34:35] op_sel:[1,0,0] op_sel_hi:[1,1,1]
	v_pk_mul_f32 v[20:21], v[20:21], v[168:169]
	v_add_f32_dpp v28, v46, v34 row_half_mirror row_mask:0xf bank_mask:0xf
	v_add_f32_dpp v151, v47, v35 row_half_mirror row_mask:0xf bank_mask:0xf
	v_pk_mul_f32 v[22:23], v[22:23], v[170:171]
	v_add_f32_dpp v28, v28, v28 row_ror:8 row_mask:0xf bank_mask:0xf
	v_pk_mul_f32 v[24:25], v[24:25], v[168:169]
	v_pk_mul_f32 v[26:27], v[26:27], v[170:171]
	v_add_f32_dpp v28, v28, v28 quad_perm:[1,0,3,2] row_mask:0xf bank_mask:0xf
	v_pk_fma_f32 v[20:21], v[180:181], v[8:9], v[20:21] op_sel_hi:[1,0,1]
	v_pk_fma_f32 v[22:23], v[182:183], v[8:9], v[22:23] op_sel_hi:[1,0,1]
	v_add_f32_dpp v28, v28, v28 quad_perm:[2,3,0,1] row_mask:0xf bank_mask:0xf
	v_pk_fma_f32 v[24:25], v[180:181], v[10:11], v[24:25] op_sel_hi:[1,0,1]
	v_pk_fma_f32 v[26:27], v[182:183], v[10:11], v[26:27] op_sel_hi:[1,0,1]
	v_mov_b32_dpp v30, v28 row_half_mirror row_mask:0xf bank_mask:0xf
	v_fmac_f32_e32 v151, 0x3e000000, v9
	v_pk_fma_f32 v[20:21], v[88:89], v[28:29], v[20:21] op_sel_hi:[1,0,1] neg_lo:[0,1,0] neg_hi:[0,1,0]
	v_pk_fma_f32 v[22:23], v[90:91], v[28:29], v[22:23] op_sel_hi:[1,0,1] neg_lo:[0,1,0] neg_hi:[0,1,0]
	v_pk_fma_f32 v[24:25], v[88:89], v[30:31], v[24:25] op_sel_hi:[1,0,1] neg_lo:[0,1,0] neg_hi:[0,1,0]
	v_pk_fma_f32 v[26:27], v[90:91], v[30:31], v[26:27] op_sel_hi:[1,0,1] neg_lo:[0,1,0] neg_hi:[0,1,0]
	ds_write_b32 v102, v163 offset:2816
	ds_read_b128 v[144:147], v195 offset:7424
	ds_read_b128 v[156:159], v195 offset:15616
	ds_read_b128 v[180:183], v195 offset:23808
	ds_read_b128 v[88:91], v195 offset:40192
	ds_read_b64 v[8:9], v196 offset:14848
	ds_read_b32 v10, v36 offset:14848
	s_waitcnt lgkmcnt(7)
	v_pk_mul_f32 v[46:47], v[24:25], v[140:141] op_sel_hi:[0,1]
	v_pk_mul_f32 v[34:35], v[20:21], v[140:141] op_sel_hi:[0,1]
	v_pk_fma_f32 v[46:47], v[24:25], v[142:143], v[46:47] op_sel:[1,0,0] op_sel_hi:[1,1,1]
	v_pk_fma_f32 v[34:35], v[20:21], v[142:143], v[34:35] op_sel:[1,0,0] op_sel_hi:[1,1,1]
	v_pk_fma_f32 v[46:47], v[26:27], v[152:153], v[46:47] op_sel_hi:[0,1,1]
	v_pk_fma_f32 v[34:35], v[22:23], v[152:153], v[34:35] op_sel_hi:[0,1,1]
	v_pk_fma_f32 v[46:47], v[26:27], v[154:155], v[46:47] op_sel:[1,0,0] op_sel_hi:[1,1,1]
	v_pk_fma_f32 v[34:35], v[22:23], v[154:155], v[34:35] op_sel:[1,0,0] op_sel_hi:[1,1,1]
	v_pk_fma_f32 v[20:21], v[176:177], v[4:5], v[20:21] op_sel_hi:[1,0,1]
	v_add_f32_dpp v28, v46, v34 row_half_mirror row_mask:0xf bank_mask:0xf
	v_add_f32_dpp v172, v47, v35 row_half_mirror row_mask:0xf bank_mask:0xf
	v_pk_fma_f32 v[22:23], v[178:179], v[4:5], v[22:23] op_sel_hi:[1,0,1]
	v_add_f32_dpp v28, v28, v28 row_ror:8 row_mask:0xf bank_mask:0xf
	v_pk_fma_f32 v[24:25], v[176:177], v[6:7], v[24:25] op_sel_hi:[1,0,1]
	v_pk_fma_f32 v[26:27], v[178:179], v[6:7], v[26:27] op_sel_hi:[1,0,1]
	v_add_f32_dpp v28, v28, v28 quad_perm:[1,0,3,2] row_mask:0xf bank_mask:0xf
	v_fmac_f32_e32 v172, 0x3e000000, v5
	v_add_f32_dpp v160, v148, v148 row_ror:8 row_mask:0xf bank_mask:0x3
	v_add_f32_dpp v28, v28, v28 quad_perm:[2,3,0,1] row_mask:0xf bank_mask:0xf
	v_pk_fma_f32 v[20:21], v[84:85], v[28:29], v[20:21] op_sel_hi:[1,0,1] neg_lo:[0,1,0] neg_hi:[0,1,0]
	v_pk_fma_f32 v[22:23], v[86:87], v[28:29], v[22:23] op_sel_hi:[1,0,1] neg_lo:[0,1,0] neg_hi:[0,1,0]
	v_mov_b32_dpp v30, v28 row_half_mirror row_mask:0xf bank_mask:0xf
	v_pk_fma_f32 v[24:25], v[84:85], v[30:31], v[24:25] op_sel_hi:[1,0,1] neg_lo:[0,1,0] neg_hi:[0,1,0]
	v_pk_fma_f32 v[26:27], v[86:87], v[30:31], v[26:27] op_sel_hi:[1,0,1] neg_lo:[0,1,0] neg_hi:[0,1,0]
	v_add_f32_dpp v160, v149, v149 row_ror:8 row_mask:0xf bank_mask:0xc
	v_add_f32_dpp v161, v150, v150 row_ror:8 row_mask:0xf bank_mask:0x3
	ds_read_b128 v[140:143], v195 offset:7680
	ds_read_b128 v[152:155], v195 offset:15872
	ds_read_b128 v[176:179], v195 offset:24064
	ds_read_b128 v[84:87], v195 offset:40448
	ds_read_b64 v[4:5], v196 offset:15360
	ds_read_b32 v6, v36 offset:15360
	s_waitcnt lgkmcnt(6)
	v_pk_mul_f32 v[46:47], v[24:25], v[144:145] op_sel_hi:[0,1]
	v_pk_mul_f32 v[34:35], v[20:21], v[144:145] op_sel_hi:[0,1]
	v_pk_fma_f32 v[46:47], v[24:25], v[146:147], v[46:47] op_sel:[1,0,0] op_sel_hi:[1,1,1]
	v_pk_fma_f32 v[34:35], v[20:21], v[146:147], v[34:35] op_sel:[1,0,0] op_sel_hi:[1,1,1]
	v_pk_fma_f32 v[46:47], v[26:27], v[156:157], v[46:47] op_sel_hi:[0,1,1]
	v_pk_fma_f32 v[34:35], v[22:23], v[156:157], v[34:35] op_sel_hi:[0,1,1]
	v_pk_fma_f32 v[46:47], v[26:27], v[158:159], v[46:47] op_sel:[1,0,0] op_sel_hi:[1,1,1]
	v_pk_fma_f32 v[34:35], v[22:23], v[158:159], v[34:35] op_sel:[1,0,0] op_sel_hi:[1,1,1]
	v_pk_fma_f32 v[20:21], v[180:181], v[8:9], v[20:21] op_sel_hi:[1,0,1]
	v_add_f32_dpp v28, v46, v34 row_half_mirror row_mask:0xf bank_mask:0xf
	v_add_f32_dpp v173, v47, v35 row_half_mirror row_mask:0xf bank_mask:0xf
	v_pk_fma_f32 v[22:23], v[182:183], v[8:9], v[22:23] op_sel_hi:[1,0,1]
	v_add_f32_dpp v28, v28, v28 row_ror:8 row_mask:0xf bank_mask:0xf
	v_pk_fma_f32 v[24:25], v[180:181], v[10:11], v[24:25] op_sel_hi:[1,0,1]
	v_pk_fma_f32 v[26:27], v[182:183], v[10:11], v[26:27] op_sel_hi:[1,0,1]
	v_add_f32_dpp v28, v28, v28 quad_perm:[1,0,3,2] row_mask:0xf bank_mask:0xf
	v_fmac_f32_e32 v173, 0x3e000000, v9
	v_add_f32_dpp v161, v151, v151 row_ror:8 row_mask:0xf bank_mask:0xc
	v_add_f32_dpp v28, v28, v28 quad_perm:[2,3,0,1] row_mask:0xf bank_mask:0xf
	v_pk_fma_f32 v[20:21], v[88:89], v[28:29], v[20:21] op_sel_hi:[1,0,1] neg_lo:[0,1,0] neg_hi:[0,1,0]
	v_pk_fma_f32 v[22:23], v[90:91], v[28:29], v[22:23] op_sel_hi:[1,0,1] neg_lo:[0,1,0] neg_hi:[0,1,0]
	v_mov_b32_dpp v30, v28 row_half_mirror row_mask:0xf bank_mask:0xf
	v_pk_fma_f32 v[24:25], v[88:89], v[30:31], v[24:25] op_sel_hi:[1,0,1] neg_lo:[0,1,0] neg_hi:[0,1,0]
	v_pk_fma_f32 v[26:27], v[90:91], v[30:31], v[26:27] op_sel_hi:[1,0,1] neg_lo:[0,1,0] neg_hi:[0,1,0]
	v_add_f32_dpp v160, v160, v160 quad_perm:[1,0,3,2] row_mask:0xf bank_mask:0xf
	v_add_f32_dpp v161, v161, v161 quad_perm:[1,0,3,2] row_mask:0xf bank_mask:0xf
	ds_read_b128 v[144:147], v195 offset:7936
	ds_read_b128 v[156:159], v195 offset:16128
	ds_read_b128 v[168:171], v195 offset:32512
	ds_read_b128 v[180:183], v195 offset:24320
	ds_read_b128 v[88:91], v195 offset:40704
	ds_read_b64 v[8:9], v196 offset:15872
	ds_read_b32 v10, v36 offset:15872
	s_waitcnt lgkmcnt(7)
	v_pk_mul_f32 v[46:47], v[24:25], v[140:141] op_sel_hi:[0,1]
	v_pk_mul_f32 v[34:35], v[20:21], v[140:141] op_sel_hi:[0,1]
	v_pk_fma_f32 v[46:47], v[24:25], v[142:143], v[46:47] op_sel:[1,0,0] op_sel_hi:[1,1,1]
	v_pk_fma_f32 v[34:35], v[20:21], v[142:143], v[34:35] op_sel:[1,0,0] op_sel_hi:[1,1,1]
	v_pk_fma_f32 v[46:47], v[26:27], v[152:153], v[46:47] op_sel_hi:[0,1,1]
	v_pk_fma_f32 v[34:35], v[22:23], v[152:153], v[34:35] op_sel_hi:[0,1,1]
	v_pk_fma_f32 v[46:47], v[26:27], v[154:155], v[46:47] op_sel:[1,0,0] op_sel_hi:[1,1,1]
	v_pk_fma_f32 v[34:35], v[22:23], v[154:155], v[34:35] op_sel:[1,0,0] op_sel_hi:[1,1,1]
	v_pk_fma_f32 v[20:21], v[176:177], v[4:5], v[20:21] op_sel_hi:[1,0,1]
	v_add_f32_dpp v28, v46, v34 row_half_mirror row_mask:0xf bank_mask:0xf
	v_add_f32_dpp v174, v47, v35 row_half_mirror row_mask:0xf bank_mask:0xf
	v_pk_fma_f32 v[22:23], v[178:179], v[4:5], v[22:23] op_sel_hi:[1,0,1]
	v_add_f32_dpp v28, v28, v28 row_ror:8 row_mask:0xf bank_mask:0xf
	v_pk_fma_f32 v[24:25], v[176:177], v[6:7], v[24:25] op_sel_hi:[1,0,1]
	v_pk_fma_f32 v[26:27], v[178:179], v[6:7], v[26:27] op_sel_hi:[1,0,1]
	v_add_f32_dpp v28, v28, v28 quad_perm:[1,0,3,2] row_mask:0xf bank_mask:0xf
	v_fmac_f32_e32 v174, 0x3e000000, v5
	v_add_f32_dpp v160, v160, v160 quad_perm:[2,3,0,1] row_mask:0xf bank_mask:0xf
	v_add_f32_dpp v28, v28, v28 quad_perm:[2,3,0,1] row_mask:0xf bank_mask:0xf
	v_pk_fma_f32 v[20:21], v[84:85], v[28:29], v[20:21] op_sel_hi:[1,0,1] neg_lo:[0,1,0] neg_hi:[0,1,0]
	v_pk_fma_f32 v[22:23], v[86:87], v[28:29], v[22:23] op_sel_hi:[1,0,1] neg_lo:[0,1,0] neg_hi:[0,1,0]
	v_mov_b32_dpp v30, v28 row_half_mirror row_mask:0xf bank_mask:0xf
	v_pk_fma_f32 v[24:25], v[84:85], v[30:31], v[24:25] op_sel_hi:[1,0,1] neg_lo:[0,1,0] neg_hi:[0,1,0]
	v_pk_fma_f32 v[26:27], v[86:87], v[30:31], v[26:27] op_sel_hi:[1,0,1] neg_lo:[0,1,0] neg_hi:[0,1,0]
	v_add_f32_dpp v161, v161, v161 quad_perm:[2,3,0,1] row_mask:0xf bank_mask:0xf
	ds_write_b32 v102, v160 offset:3072
	s_waitcnt lgkmcnt(1)
	v_pk_mul_f32 v[46:47], v[24:25], v[144:145] op_sel_hi:[0,1]
	v_pk_mul_f32 v[34:35], v[20:21], v[144:145] op_sel_hi:[0,1]
	v_pk_fma_f32 v[46:47], v[24:25], v[146:147], v[46:47] op_sel:[1,0,0] op_sel_hi:[1,1,1]
	v_pk_fma_f32 v[34:35], v[20:21], v[146:147], v[34:35] op_sel:[1,0,0] op_sel_hi:[1,1,1]
	v_pk_fma_f32 v[46:47], v[26:27], v[156:157], v[46:47] op_sel_hi:[0,1,1]
	v_pk_fma_f32 v[34:35], v[22:23], v[156:157], v[34:35] op_sel_hi:[0,1,1]
	v_pk_fma_f32 v[46:47], v[26:27], v[158:159], v[46:47] op_sel:[1,0,0] op_sel_hi:[1,1,1]
	v_pk_fma_f32 v[34:35], v[22:23], v[158:159], v[34:35] op_sel:[1,0,0] op_sel_hi:[1,1,1]
	v_pk_mul_f32 v[20:21], v[20:21], v[168:169]
	v_add_f32_dpp v28, v46, v34 row_half_mirror row_mask:0xf bank_mask:0xf
	v_add_f32_dpp v175, v47, v35 row_half_mirror row_mask:0xf bank_mask:0xf
	v_pk_mul_f32 v[22:23], v[22:23], v[170:171]
	v_add_f32_dpp v28, v28, v28 row_ror:8 row_mask:0xf bank_mask:0xf
	v_pk_mul_f32 v[24:25], v[24:25], v[168:169]
	v_pk_mul_f32 v[26:27], v[26:27], v[170:171]
	v_add_f32_dpp v28, v28, v28 quad_perm:[1,0,3,2] row_mask:0xf bank_mask:0xf
	v_pk_fma_f32 v[20:21], v[180:181], v[8:9], v[20:21] op_sel_hi:[1,0,1]
	v_pk_fma_f32 v[22:23], v[182:183], v[8:9], v[22:23] op_sel_hi:[1,0,1]
	v_add_f32_dpp v28, v28, v28 quad_perm:[2,3,0,1] row_mask:0xf bank_mask:0xf
	v_pk_fma_f32 v[24:25], v[180:181], v[10:11], v[24:25] op_sel_hi:[1,0,1]
	v_pk_fma_f32 v[26:27], v[182:183], v[10:11], v[26:27] op_sel_hi:[1,0,1]
	v_mov_b32_dpp v30, v28 row_half_mirror row_mask:0xf bank_mask:0xf
	v_fmac_f32_e32 v175, 0x3e000000, v9
	v_pk_fma_f32 v[20:21], v[88:89], v[28:29], v[20:21] op_sel_hi:[1,0,1] neg_lo:[0,1,0] neg_hi:[0,1,0]
	v_pk_fma_f32 v[22:23], v[90:91], v[28:29], v[22:23] op_sel_hi:[1,0,1] neg_lo:[0,1,0] neg_hi:[0,1,0]
	v_pk_fma_f32 v[24:25], v[88:89], v[30:31], v[24:25] op_sel_hi:[1,0,1] neg_lo:[0,1,0] neg_hi:[0,1,0]
	v_pk_fma_f32 v[26:27], v[90:91], v[30:31], v[26:27] op_sel_hi:[1,0,1] neg_lo:[0,1,0] neg_hi:[0,1,0]
	ds_write_b32 v102, v161 offset:3328
	v_add_f32_dpp v162, v172, v172 row_ror:8 row_mask:0xf bank_mask:0x3
	v_add_f32_dpp v162, v173, v173 row_ror:8 row_mask:0xf bank_mask:0xc
	v_add_f32_dpp v163, v174, v174 row_ror:8 row_mask:0xf bank_mask:0x3
	v_add_f32_dpp v163, v175, v175 row_ror:8 row_mask:0xf bank_mask:0xc
	v_add_f32_dpp v162, v162, v162 quad_perm:[1,0,3,2] row_mask:0xf bank_mask:0xf
	s_nop 0
	v_add_f32_dpp v163, v163, v163 quad_perm:[1,0,3,2] row_mask:0xf bank_mask:0xf
	v_add_f32_dpp v162, v162, v162 quad_perm:[2,3,0,1] row_mask:0xf bank_mask:0xf
	s_nop 0
	v_add_f32_dpp v163, v163, v163 quad_perm:[2,3,0,1] row_mask:0xf bank_mask:0xf
	ds_write_b32 v102, v162 offset:3584
	ds_write_b32 v102, v163 offset:3840
	s_waitcnt lgkmcnt(0)
	s_barrier
	s_add_i32 s8, s8, 1
	s_cmp_eq_u32 s8, 64
	s_cbranch_scc0 .Lrw_scan_loop
	s_setprio 0
	s_branch .LBB0_183
